# cache policy: prologue 16-byte stores of converted weights / bf16 p / S5 operators also nt (write without allocating in L2)
# speedup vs baseline: 1.0041x; 1.0041x over previous
.LBB0_8:
	v_ashrrev_i32_e32 v17, 31, v16
	s_waitcnt vmcnt(30)
	ds_write2_b32 v35, v18, v19 offset1:66
	s_waitcnt vmcnt(28)
	ds_write2_b32 v35, v20, v21 offset0:132 offset1:198
	s_waitcnt vmcnt(26)
	ds_write2_b32 v84, v22, v23 offset0:8 offset1:74
	s_waitcnt vmcnt(24)
	ds_write2_b32 v84, v24, v25 offset0:140 offset1:206
	s_waitcnt vmcnt(22)
	ds_write2_b32 v85, v26, v27 offset0:16 offset1:82
	s_waitcnt vmcnt(20)
	ds_write2_b32 v85, v28, v29 offset0:148 offset1:214
	s_waitcnt vmcnt(18)
	ds_write2_b32 v86, v30, v31 offset0:24 offset1:90
	s_waitcnt vmcnt(16)
	ds_write2_b32 v86, v32, v33 offset0:156 offset1:222
	s_waitcnt vmcnt(14)
	ds_write2_b32 v87, v40, v41 offset0:32 offset1:98
	s_waitcnt vmcnt(12)
	ds_write2_b32 v87, v42, v43 offset0:164 offset1:230
	s_waitcnt vmcnt(10)
	ds_write2_b32 v88, v44, v45 offset0:40 offset1:106
	s_waitcnt vmcnt(8)
	ds_write2_b32 v88, v46, v47 offset0:172 offset1:238
	s_waitcnt vmcnt(6)
	ds_write2_b32 v89, v48, v49 offset0:48 offset1:114
	s_waitcnt vmcnt(4)
	ds_write2_b32 v89, v50, v51 offset0:180 offset1:246
	s_waitcnt vmcnt(2)
	ds_write2_b32 v90, v52, v53 offset0:56 offset1:122
	s_waitcnt vmcnt(0)
	ds_write2_b32 v90, v54, v55 offset0:188 offset1:254
	v_lshl_add_u64 v[10:11], v[16:17], 1, v[10:11]
	v_mov_b32_e32 v9, v5
	s_waitcnt lgkmcnt(0)
	v_lshl_add_u64 v[16:17], v[10:11], 0, v[8:9]
	v_or_b32_e32 v10, v14, v37
	ds_read2_b32 v[12:13], v39 offset1:33
	v_ashrrev_i32_e32 v11, 31, v10
	s_waitcnt lgkmcnt(0)
	v_cvt_pk_bf16_f32 v18, v12, v13
	ds_read2_b32 v[12:13], v39 offset0:66 offset1:99
	v_lshlrev_b64 v[10:11], 11, v[10:11]
	s_waitcnt lgkmcnt(0)
	v_cvt_pk_bf16_f32 v19, v12, v13
	ds_read2_b32 v[12:13], v39 offset0:132 offset1:165
	s_waitcnt lgkmcnt(0)
	v_cvt_pk_bf16_f32 v20, v12, v13
	v_lshl_add_u64 v[10:11], v[16:17], 0, v[10:11]
	ds_read2_b32 v[12:13], v39 offset0:198 offset1:231
	s_waitcnt lgkmcnt(0)
	v_cvt_pk_bf16_f32 v21, v12, v13
	global_store_dwordx4 v[10:11], v[18:21], off nt
	ds_read2_b32 v[12:13], v39 offset0:8 offset1:41
	s_waitcnt lgkmcnt(0)
	v_cvt_pk_bf16_f32 v10, v12, v13
	ds_read2_b32 v[12:13], v39 offset0:74 offset1:107
	v_or_b32_e32 v20, v14, v77
	v_ashrrev_i32_e32 v21, 31, v20
	v_lshlrev_b64 v[20:21], 11, v[20:21]
	s_waitcnt lgkmcnt(0)
	v_cvt_pk_bf16_f32 v11, v12, v13
	ds_read2_b32 v[12:13], v39 offset0:140 offset1:173
	v_lshl_add_u64 v[20:21], v[16:17], 0, v[20:21]
	s_waitcnt lgkmcnt(0)
	v_cvt_pk_bf16_f32 v12, v12, v13
	ds_read2_b32 v[18:19], v39 offset0:206 offset1:239
	s_waitcnt lgkmcnt(0)
	v_cvt_pk_bf16_f32 v13, v18, v19
	global_store_dwordx4 v[20:21], v[10:13], off nt
	v_or_b32_e32 v20, v14, v78
	ds_read2_b32 v[18:19], v39 offset0:16 offset1:49
	s_waitcnt lgkmcnt(0)
	v_cvt_pk_bf16_f32 v10, v18, v19
	ds_read2_b32 v[12:13], v39 offset0:82 offset1:115
	v_ashrrev_i32_e32 v21, 31, v20
	s_waitcnt lgkmcnt(0)
	v_cvt_pk_bf16_f32 v11, v12, v13
	ds_read2_b32 v[12:13], v39 offset0:148 offset1:181
	v_lshlrev_b64 v[20:21], 11, v[20:21]
	v_or_b32_e32 v14, v14, v79
	s_waitcnt lgkmcnt(0)
	v_cvt_pk_bf16_f32 v12, v12, v13
	ds_read2_b32 v[18:19], v39 offset0:214 offset1:247
	s_waitcnt lgkmcnt(0)
	v_cvt_pk_bf16_f32 v13, v18, v19
	v_lshl_add_u64 v[20:21], v[16:17], 0, v[20:21]
	v_ashrrev_i32_e32 v15, 31, v14
	ds_read2_b32 v[18:19], v39 offset0:24 offset1:57
	global_store_dwordx4 v[20:21], v[10:13], off nt
	v_lshlrev_b64 v[14:15], 11, v[14:15]
	v_lshl_add_u64 v[14:15], v[16:17], 0, v[14:15]
	s_waitcnt lgkmcnt(0)
	v_cvt_pk_bf16_f32 v10, v18, v19
	ds_read2_b32 v[12:13], v39 offset0:90 offset1:123
	s_waitcnt lgkmcnt(0)
	v_cvt_pk_bf16_f32 v11, v12, v13
	ds_read2_b32 v[12:13], v39 offset0:156 offset1:189
	s_waitcnt lgkmcnt(0)
	v_cvt_pk_bf16_f32 v12, v12, v13
	ds_read2_b32 v[18:19], v39 offset0:222 offset1:255
	s_waitcnt lgkmcnt(0)
	v_cvt_pk_bf16_f32 v13, v18, v19
	global_store_dwordx4 v[14:15], v[10:13], off nt
	s_waitcnt lgkmcnt(0)

.LBB0_10:
	s_mov_b32 s16, 0x2aaaaaab
	v_mul_hi_i32 v9, v151, s16
	v_lshrrev_b32_e32 v10, 31, v9
	v_ashrrev_i32_e32 v9, 10, v9
	v_add_u32_e32 v12, v9, v10
	s_mov_b32 s16, 0x1800000
	v_mul_i32_i24_e32 v14, 0x1800, v12
	v_mad_i64_i32 v[10:11], s[16:17], v12, s16, v[6:7]
	v_sub_u32_e32 v15, v151, v14
	s_movk_i32 s16, 0x27f
	v_ashrrev_i32_e32 v13, 31, v12
	v_cmp_lt_i32_e32 vcc, s16, v15
	s_and_saveexec_b64 s[16:17], vcc
	s_xor_b64 s[16:17], exec, s[16:17]
	s_cbranch_execz .LBB0_42
	s_movk_i32 s18, 0x2ff
	v_cmp_lt_u32_e32 vcc, s18, v15
	s_and_saveexec_b64 s[18:19], vcc
	s_xor_b64 s[18:19], exec, s[18:19]
	s_cbranch_execz .LBB0_39
	s_movk_i32 s20, 0x4ff
	v_cmp_lt_u32_e32 vcc, s20, v15
	s_and_saveexec_b64 s[20:21], vcc
	s_xor_b64 s[20:21], exec, s[20:21]
	s_cbranch_execz .LBB0_34
	s_movk_i32 s22, 0xfff
	v_cmp_lt_u32_e32 vcc, s22, v15
	s_and_saveexec_b64 s[22:23], vcc
	s_xor_b64 s[22:23], exec, s[22:23]
	s_cbranch_execz .LBB0_25
	s_movk_i32 s24, 0x157f
	v_lshlrev_b32_e32 v9, 1, v14
	v_cmp_lt_u32_e32 vcc, s24, v15
	v_sub_u32_e32 v9, v82, v9
	s_and_saveexec_b64 s[24:25], vcc
	s_xor_b64 s[24:25], exec, s[24:25]
	s_cbranch_execz .LBB0_22
	v_lshlrev_b32_e32 v14, 5, v14
	s_movk_i32 s26, 0x177f
	v_sub_u32_e32 v14, v80, v14
	v_cmp_lt_u32_e32 vcc, s26, v15
	v_and_b32_e32 v15, 0x3e0, v14
	v_lshlrev_b32_e32 v14, 2, v15
	v_or_b32_e32 v55, v15, v37
	v_or_b32_e32 v54, v15, v77
	v_or_b32_e32 v53, v15, v78
	v_or_b32_e32 v52, v15, v79
	s_and_saveexec_b64 s[26:27], vcc
	s_xor_b64 s[26:27], exec, s[26:27]
	s_cbranch_execz .LBB0_17
	v_readlane_b32 s36, v247, 26
	v_lshlrev_b64 v[12:13], 20, v[12:13]
	v_readlane_b32 s48, v247, 38
	v_readlane_b32 s49, v247, 39
	v_and_b32_e32 v15, 0x1c0, v9
	v_bitop3_b32 v16, v15, v3, s30 bitop3:0xde
	v_lshl_add_u64 v[12:13], s[48:49], 0, v[12:13]
	v_mov_b32_e32 v15, v5
	v_lshl_add_u64 v[12:13], v[12:13], 0, v[14:15]
	v_lshl_add_u64 v[12:13], v[12:13], 0, v[4:5]
	v_lshlrev_b32_e32 v14, 12, v16
	v_lshl_add_u64 v[12:13], v[12:13], 0, v[14:15]
	v_add_co_u32_e32 v14, vcc, s31, v12
	v_bitop3_b32 v9, v9, s30, v83 bitop3:0x6c
	s_nop 0
	v_addc_co_u32_e32 v15, vcc, 0, v13, vcc
	v_add_co_u32_e32 v16, vcc, s34, v12
	s_mov_b64 s[84:85], 0x1780000
	s_nop 0
	v_addc_co_u32_e32 v17, vcc, 0, v13, vcc
	v_add_co_u32_e32 v18, vcc, s3, v12
	v_readlane_b32 s37, v247, 27
	s_nop 0
	v_addc_co_u32_e32 v19, vcc, 0, v13, vcc
	v_add_co_u32_e32 v20, vcc, s35, v12
	v_readlane_b32 s38, v247, 28
	s_nop 0
	v_addc_co_u32_e32 v21, vcc, 0, v13, vcc
	v_add_co_u32_e32 v22, vcc, s52, v12
	v_readlane_b32 s39, v247, 29
	s_nop 0
	v_addc_co_u32_e32 v23, vcc, 0, v13, vcc
	v_add_co_u32_e32 v24, vcc, s53, v12
	v_readlane_b32 s40, v247, 30
	s_nop 0
	v_addc_co_u32_e32 v25, vcc, 0, v13, vcc
	v_add_co_u32_e32 v26, vcc, s54, v12
	v_readlane_b32 s41, v247, 31
	s_nop 0
	v_addc_co_u32_e32 v27, vcc, 0, v13, vcc
	global_load_dword v30, v[12:13], off nt
	global_load_dword v31, v[14:15], off nt
	global_load_dword v32, v[16:17], off nt
	global_load_dword v33, v[18:19], off nt
	global_load_dword v40, v[20:21], off nt
	global_load_dword v41, v[22:23], off nt
	global_load_dword v42, v[24:25], off nt
	global_load_dword v43, v[26:27], off nt
	v_add_co_u32_e32 v14, vcc, s55, v12
	v_readlane_b32 s42, v247, 32
	s_nop 0
	v_addc_co_u32_e32 v15, vcc, 0, v13, vcc
	v_add_co_u32_e32 v16, vcc, s56, v12
	v_readlane_b32 s43, v247, 33
	s_nop 0
	v_addc_co_u32_e32 v17, vcc, 0, v13, vcc
	v_add_co_u32_e32 v18, vcc, s57, v12
	v_readlane_b32 s44, v247, 34
	s_nop 0
	v_addc_co_u32_e32 v19, vcc, 0, v13, vcc
	v_add_co_u32_e32 v20, vcc, s58, v12
	v_readlane_b32 s45, v247, 35
	s_nop 0
	v_addc_co_u32_e32 v21, vcc, 0, v13, vcc
	v_add_co_u32_e32 v22, vcc, s59, v12
	v_readlane_b32 s46, v247, 36
	s_nop 0
	v_addc_co_u32_e32 v23, vcc, 0, v13, vcc
	v_add_co_u32_e32 v24, vcc, s60, v12
	v_readlane_b32 s47, v247, 37
	s_nop 0
	v_addc_co_u32_e32 v25, vcc, 0, v13, vcc
	v_add_co_u32_e32 v26, vcc, s61, v12
	v_readlane_b32 s50, v247, 40
	s_nop 0
	v_addc_co_u32_e32 v27, vcc, 0, v13, vcc
	v_add_co_u32_e32 v28, vcc, s62, v12
	v_readlane_b32 s51, v247, 41
	s_nop 0
	v_addc_co_u32_e32 v29, vcc, 0, v13, vcc
	global_load_dword v44, v[14:15], off nt
	global_load_dword v45, v[16:17], off nt
	global_load_dword v46, v[18:19], off nt
	global_load_dword v47, v[20:21], off nt
	global_load_dword v48, v[22:23], off nt
	global_load_dword v49, v[24:25], off nt
	global_load_dword v50, v[26:27], off nt
	global_load_dword v51, v[28:29], off nt
	v_add_co_u32_e32 v14, vcc, s63, v12
	s_nop 1
	v_addc_co_u32_e32 v15, vcc, 0, v13, vcc
	v_add_co_u32_e32 v16, vcc, s64, v12
	s_nop 1
	v_addc_co_u32_e32 v17, vcc, 0, v13, vcc
	v_add_co_u32_e32 v18, vcc, s65, v12
	s_nop 1
	v_addc_co_u32_e32 v19, vcc, 0, v13, vcc
	v_add_co_u32_e32 v20, vcc, s67, v12
	s_nop 1
	v_addc_co_u32_e32 v21, vcc, 0, v13, vcc
	v_add_co_u32_e32 v22, vcc, s68, v12
	s_nop 1
	v_addc_co_u32_e32 v23, vcc, 0, v13, vcc
	v_add_co_u32_e32 v24, vcc, s69, v12
	s_nop 1
	v_addc_co_u32_e32 v25, vcc, 0, v13, vcc
	v_add_co_u32_e32 v26, vcc, s70, v12
	s_nop 1
	v_addc_co_u32_e32 v27, vcc, 0, v13, vcc
	v_add_co_u32_e32 v28, vcc, s71, v12
	s_nop 1
	v_addc_co_u32_e32 v29, vcc, 0, v13, vcc
	global_load_dword v56, v[14:15], off nt
	global_load_dword v57, v[16:17], off nt
	global_load_dword v58, v[18:19], off nt
	global_load_dword v59, v[20:21], off nt
	global_load_dword v60, v[22:23], off nt
	global_load_dword v61, v[24:25], off nt
	global_load_dword v62, v[26:27], off nt
	s_nop 0
	global_load_dword v28, v[28:29], off nt
	v_add_co_u32_e32 v14, vcc, s72, v12
	s_nop 1
	v_addc_co_u32_e32 v15, vcc, 0, v13, vcc
	v_add_co_u32_e32 v16, vcc, s73, v12
	s_nop 1
	v_addc_co_u32_e32 v17, vcc, 0, v13, vcc
	v_add_co_u32_e32 v18, vcc, s74, v12
	s_nop 1
	v_addc_co_u32_e32 v19, vcc, 0, v13, vcc
	v_add_co_u32_e32 v20, vcc, s75, v12
	s_nop 1
	v_addc_co_u32_e32 v21, vcc, 0, v13, vcc
	v_add_co_u32_e32 v22, vcc, s76, v12
	s_nop 1
	v_addc_co_u32_e32 v23, vcc, 0, v13, vcc
	v_add_co_u32_e32 v24, vcc, s77, v12
	s_nop 1
	v_addc_co_u32_e32 v25, vcc, 0, v13, vcc
	v_add_co_u32_e32 v26, vcc, s78, v12
	s_nop 1
	v_addc_co_u32_e32 v27, vcc, 0, v13, vcc
	v_add_co_u32_e32 v12, vcc, s79, v12
	s_nop 1
	v_addc_co_u32_e32 v13, vcc, 0, v13, vcc
	global_load_dword v14, v[14:15], off nt
	s_nop 0
	global_load_dword v15, v[16:17], off nt
	s_nop 0
	global_load_dword v16, v[18:19], off nt
	global_load_dword v17, v[20:21], off nt
	s_nop 0
	global_load_dword v18, v[22:23], off nt
	global_load_dword v19, v[24:25], off nt
	global_load_dword v20, v[26:27], off nt
	s_nop 0
	global_load_dword v12, v[12:13], off nt
	s_waitcnt vmcnt(30)
	ds_write2_b32 v35, v30, v31 offset1:66
	s_waitcnt vmcnt(28)
	ds_write2_b32 v35, v32, v33 offset0:132 offset1:198
	s_waitcnt vmcnt(26)
	ds_write2_b32 v84, v40, v41 offset0:8 offset1:74
	s_waitcnt vmcnt(24)
	ds_write2_b32 v84, v42, v43 offset0:140 offset1:206
	s_waitcnt vmcnt(22)
	ds_write2_b32 v85, v44, v45 offset0:16 offset1:82
	s_waitcnt vmcnt(20)
	ds_write2_b32 v85, v46, v47 offset0:148 offset1:214
	s_waitcnt vmcnt(18)
	ds_write2_b32 v86, v48, v49 offset0:24 offset1:90
	s_waitcnt vmcnt(16)
	ds_write2_b32 v86, v50, v51 offset0:156 offset1:222
	s_waitcnt vmcnt(14)
	ds_write2_b32 v87, v56, v57 offset0:32 offset1:98
	s_waitcnt vmcnt(12)
	ds_write2_b32 v87, v58, v59 offset0:164 offset1:230
	s_waitcnt vmcnt(10)
	ds_write2_b32 v88, v60, v61 offset0:40 offset1:106
	s_waitcnt vmcnt(8)
	ds_write2_b32 v88, v62, v28 offset0:172 offset1:238
	s_waitcnt vmcnt(6)
	ds_write2_b32 v89, v14, v15 offset0:48 offset1:114
	s_waitcnt vmcnt(4)
	ds_write2_b32 v89, v16, v17 offset0:180 offset1:246
	s_waitcnt vmcnt(2)
	ds_write2_b32 v90, v18, v19 offset0:56 offset1:122
	s_waitcnt vmcnt(0)
	ds_write2_b32 v90, v20, v12 offset0:188 offset1:254
	s_waitcnt lgkmcnt(0)
	ds_read2_b32 v[12:13], v39 offset1:33
	s_waitcnt lgkmcnt(0)
	v_cvt_pk_bf16_f32 v12, v12, v13
	ds_read2_b32 v[14:15], v39 offset0:66 offset1:99
	v_lshlrev_b32_e32 v16, 1, v9
	v_mov_b32_e32 v17, v5
	s_waitcnt lgkmcnt(0)
	v_cvt_pk_bf16_f32 v13, v14, v15
	ds_read2_b32 v[14:15], v39 offset0:132 offset1:165
	v_lshl_add_u64 v[10:11], v[10:11], 0, v[16:17]
	v_mov_b32_e32 v9, v5
	s_waitcnt lgkmcnt(0)
	v_cvt_pk_bf16_f32 v14, v14, v15
	ds_read2_b32 v[18:19], v39 offset0:198 offset1:231
	v_lshl_add_u64 v[10:11], v[10:11], 0, v[8:9]
	v_lshl_add_u64 v[16:17], v[10:11], 0, s[84:85]
	s_waitcnt lgkmcnt(0)
	v_cvt_pk_bf16_f32 v15, v18, v19
	v_lshlrev_b32_e32 v18, 9, v55
	v_mov_b32_e32 v19, v5
	ds_read2_b32 v[10:11], v39 offset0:8 offset1:41
	v_lshl_add_u64 v[18:19], v[16:17], 0, v[18:19]
	global_store_dwordx4 v[18:19], v[12:15], off nt
	s_waitcnt lgkmcnt(0)
	v_cvt_pk_bf16_f32 v10, v10, v11
	ds_read2_b32 v[12:13], v39 offset0:74 offset1:107
	s_waitcnt lgkmcnt(0)
	v_cvt_pk_bf16_f32 v11, v12, v13
	ds_read2_b32 v[12:13], v39 offset0:140 offset1:173
	v_lshlrev_b32_e32 v18, 9, v54
	v_mov_b32_e32 v19, v5
	s_waitcnt lgkmcnt(0)
	v_cvt_pk_bf16_f32 v12, v12, v13
	ds_read2_b32 v[14:15], v39 offset0:206 offset1:239
	s_waitcnt lgkmcnt(0)
	v_cvt_pk_bf16_f32 v13, v14, v15
	v_lshl_add_u64 v[18:19], v[16:17], 0, v[18:19]
	ds_read2_b32 v[14:15], v39 offset0:16 offset1:49
	global_store_dwordx4 v[18:19], v[10:13], off nt
	v_lshlrev_b32_e32 v18, 9, v53
	v_mov_b32_e32 v19, v5
	s_waitcnt lgkmcnt(0)
	v_cvt_pk_bf16_f32 v10, v14, v15
	ds_read2_b32 v[12:13], v39 offset0:82 offset1:115
	s_waitcnt lgkmcnt(0)
	v_cvt_pk_bf16_f32 v11, v12, v13
	ds_read2_b32 v[12:13], v39 offset0:148 offset1:181
	s_waitcnt lgkmcnt(0)
	v_cvt_pk_bf16_f32 v12, v12, v13
	ds_read2_b32 v[14:15], v39 offset0:214 offset1:247
	s_waitcnt lgkmcnt(0)
	v_cvt_pk_bf16_f32 v13, v14, v15
	v_lshl_add_u64 v[18:19], v[16:17], 0, v[18:19]
	ds_read2_b32 v[14:15], v39 offset0:24 offset1:57
	global_store_dwordx4 v[18:19], v[10:13], off nt
	s_waitcnt lgkmcnt(0)
	s_nop 0
	v_cvt_pk_bf16_f32 v10, v14, v15
	ds_read2_b32 v[12:13], v39 offset0:90 offset1:123
	s_waitcnt lgkmcnt(0)
	v_cvt_pk_bf16_f32 v11, v12, v13
	ds_read2_b32 v[12:13], v39 offset0:156 offset1:189
	s_waitcnt lgkmcnt(0)
	v_cvt_pk_bf16_f32 v12, v12, v13
	ds_read2_b32 v[14:15], v39 offset0:222 offset1:255
	s_waitcnt lgkmcnt(0)
	v_cvt_pk_bf16_f32 v13, v14, v15
	v_lshlrev_b32_e32 v14, 9, v52
	v_mov_b32_e32 v15, v5
	v_lshl_add_u64 v[14:15], v[16:17], 0, v[14:15]
	global_store_dwordx4 v[14:15], v[10:13], off nt
	s_waitcnt lgkmcnt(0)

.LBB0_20:
	s_waitcnt vmcnt(30)
	ds_write2_b32 v35, v14, v15 offset1:66
	s_waitcnt vmcnt(28)
	ds_write2_b32 v35, v16, v17 offset0:132 offset1:198
	s_waitcnt vmcnt(26)
	ds_write2_b32 v84, v18, v19 offset0:8 offset1:74
	s_waitcnt vmcnt(24)
	ds_write2_b32 v84, v20, v21 offset0:140 offset1:206
	s_waitcnt vmcnt(22)
	ds_write2_b32 v85, v22, v23 offset0:16 offset1:82
	s_waitcnt vmcnt(20)
	ds_write2_b32 v85, v24, v25 offset0:148 offset1:214
	s_waitcnt vmcnt(18)
	ds_write2_b32 v86, v26, v27 offset0:24 offset1:90
	s_waitcnt vmcnt(16)
	ds_write2_b32 v86, v28, v29 offset0:156 offset1:222
	s_waitcnt vmcnt(14)
	ds_write2_b32 v87, v30, v31 offset0:32 offset1:98
	s_waitcnt vmcnt(12)
	ds_write2_b32 v87, v32, v33 offset0:164 offset1:230
	s_waitcnt vmcnt(10)
	ds_write2_b32 v88, v40, v41 offset0:40 offset1:106
	s_waitcnt vmcnt(8)
	ds_write2_b32 v88, v42, v43 offset0:172 offset1:238
	s_waitcnt vmcnt(6)
	ds_write2_b32 v89, v44, v45 offset0:48 offset1:114
	s_waitcnt vmcnt(4)
	ds_write2_b32 v89, v46, v47 offset0:180 offset1:246
	s_waitcnt vmcnt(2)
	ds_write2_b32 v90, v50, v51 offset0:56 offset1:122
	s_waitcnt vmcnt(0)
	ds_write2_b32 v90, v48, v49 offset0:188 offset1:254
	s_waitcnt lgkmcnt(0)
	ds_read2_b32 v[12:13], v39 offset1:33
	s_waitcnt lgkmcnt(0)
	v_cvt_pk_bf16_f32 v12, v12, v13
	ds_read2_b32 v[14:15], v39 offset0:66 offset1:99
	v_lshlrev_b32_e32 v16, 1, v9
	v_mov_b32_e32 v17, v5
	s_waitcnt lgkmcnt(0)
	v_cvt_pk_bf16_f32 v13, v14, v15
	ds_read2_b32 v[14:15], v39 offset0:132 offset1:165
	v_lshl_add_u64 v[10:11], v[10:11], 0, v[16:17]
	v_mov_b32_e32 v9, v5
	s_waitcnt lgkmcnt(0)
	v_cvt_pk_bf16_f32 v14, v14, v15
	ds_read2_b32 v[18:19], v39 offset0:198 offset1:231
	v_lshl_add_u64 v[10:11], v[10:11], 0, v[8:9]
	s_mov_b64 s[84:85], 0x1580000
	v_lshl_add_u64 v[16:17], v[10:11], 0, s[84:85]
	s_waitcnt lgkmcnt(0)
	v_cvt_pk_bf16_f32 v15, v18, v19
	v_lshlrev_b32_e32 v18, 11, v55
	v_mov_b32_e32 v19, v5
	ds_read2_b32 v[10:11], v39 offset0:8 offset1:41
	v_lshl_add_u64 v[18:19], v[16:17], 0, v[18:19]
	global_store_dwordx4 v[18:19], v[12:15], off nt
	s_waitcnt lgkmcnt(0)
	v_cvt_pk_bf16_f32 v10, v10, v11
	ds_read2_b32 v[12:13], v39 offset0:74 offset1:107
	s_waitcnt lgkmcnt(0)
	v_cvt_pk_bf16_f32 v11, v12, v13
	ds_read2_b32 v[12:13], v39 offset0:140 offset1:173
	v_lshlrev_b32_e32 v18, 11, v54
	v_mov_b32_e32 v19, v5
	s_waitcnt lgkmcnt(0)
	v_cvt_pk_bf16_f32 v12, v12, v13
	ds_read2_b32 v[14:15], v39 offset0:206 offset1:239
	s_waitcnt lgkmcnt(0)
	v_cvt_pk_bf16_f32 v13, v14, v15
	v_lshl_add_u64 v[18:19], v[16:17], 0, v[18:19]
	ds_read2_b32 v[14:15], v39 offset0:16 offset1:49
	global_store_dwordx4 v[18:19], v[10:13], off nt
	v_lshlrev_b32_e32 v18, 11, v53
	v_mov_b32_e32 v19, v5
	s_waitcnt lgkmcnt(0)
	v_cvt_pk_bf16_f32 v10, v14, v15
	ds_read2_b32 v[12:13], v39 offset0:82 offset1:115
	s_waitcnt lgkmcnt(0)
	v_cvt_pk_bf16_f32 v11, v12, v13
	ds_read2_b32 v[12:13], v39 offset0:148 offset1:181
	s_waitcnt lgkmcnt(0)
	v_cvt_pk_bf16_f32 v12, v12, v13
	ds_read2_b32 v[14:15], v39 offset0:214 offset1:247
	s_waitcnt lgkmcnt(0)
	v_cvt_pk_bf16_f32 v13, v14, v15
	v_lshl_add_u64 v[18:19], v[16:17], 0, v[18:19]
	ds_read2_b32 v[14:15], v39 offset0:24 offset1:57
	global_store_dwordx4 v[18:19], v[10:13], off nt
	v_lshlrev_b32_e32 v18, 11, v52
	v_mov_b32_e32 v19, v5
	s_waitcnt lgkmcnt(0)
	v_cvt_pk_bf16_f32 v10, v14, v15
	ds_read2_b32 v[12:13], v39 offset0:90 offset1:123
	s_waitcnt lgkmcnt(0)
	v_cvt_pk_bf16_f32 v11, v12, v13
	ds_read2_b32 v[12:13], v39 offset0:156 offset1:189
	s_waitcnt lgkmcnt(0)
	v_cvt_pk_bf16_f32 v12, v12, v13
	ds_read2_b32 v[14:15], v39 offset0:222 offset1:255
	s_waitcnt lgkmcnt(0)
	v_cvt_pk_bf16_f32 v13, v14, v15
	v_lshl_add_u64 v[14:15], v[16:17], 0, v[18:19]
	global_store_dwordx4 v[14:15], v[10:13], off nt
	s_waitcnt lgkmcnt(0)

.LBB0_22:
	s_andn2_saveexec_b64 s[24:25], s[24:25]
	s_cbranch_execz .LBB0_24
	v_readlane_b32 s36, v247, 26
	v_lshlrev_b32_e32 v14, 5, v14
	v_readlane_b32 s42, v247, 32
	v_readlane_b32 s43, v247, 33
	v_sub_u32_e32 v14, v80, v14
	s_mov_b32 s26, 0xb00000
	v_mov_b64_e32 v[16:17], s[42:43]
	v_add_u32_e32 v9, 0x1e000, v9
	v_and_b32_e32 v30, 0x3e0, v14
	v_mad_i64_i32 v[12:13], s[26:27], v12, s26, v[16:17]
	v_and_b32_e32 v9, 0x1ffc0, v9
	v_lshlrev_b32_e32 v14, 2, v30
	v_mov_b32_e32 v15, v5
	v_or_b32_e32 v16, v9, v3
	v_lshl_add_u64 v[12:13], v[12:13], 0, v[14:15]
	v_lshl_add_u64 v[12:13], v[12:13], 0, v[4:5]
	v_lshlrev_b32_e32 v14, 12, v16
	v_lshl_add_u64 v[12:13], v[12:13], 0, v[14:15]
	v_add_co_u32_e32 v14, vcc, s31, v12
	s_mov_b64 s[26:27], 0x1000000
	s_nop 0
	v_addc_co_u32_e32 v15, vcc, 0, v13, vcc
	v_add_co_u32_e32 v16, vcc, s34, v12
	v_readlane_b32 s37, v247, 27
	s_nop 0
	v_addc_co_u32_e32 v17, vcc, 0, v13, vcc
	v_add_co_u32_e32 v18, vcc, s3, v12
	v_readlane_b32 s38, v247, 28
	s_nop 0
	v_addc_co_u32_e32 v19, vcc, 0, v13, vcc
	v_add_co_u32_e32 v20, vcc, s35, v12
	v_readlane_b32 s39, v247, 29
	s_nop 0
	v_addc_co_u32_e32 v21, vcc, 0, v13, vcc
	v_add_co_u32_e32 v22, vcc, s52, v12
	v_readlane_b32 s40, v247, 30
	s_nop 0
	v_addc_co_u32_e32 v23, vcc, 0, v13, vcc
	v_add_co_u32_e32 v24, vcc, s53, v12
	v_readlane_b32 s41, v247, 31
	s_nop 0
	v_addc_co_u32_e32 v25, vcc, 0, v13, vcc
	v_add_co_u32_e32 v26, vcc, s54, v12
	v_readlane_b32 s44, v247, 34
	s_nop 0
	v_addc_co_u32_e32 v27, vcc, 0, v13, vcc
	global_load_dword v31, v[12:13], off nt
	global_load_dword v32, v[14:15], off nt
	global_load_dword v33, v[16:17], off nt
	global_load_dword v40, v[18:19], off nt
	global_load_dword v41, v[20:21], off nt
	global_load_dword v42, v[22:23], off nt
	global_load_dword v43, v[24:25], off nt
	global_load_dword v44, v[26:27], off nt
	v_add_co_u32_e32 v14, vcc, s55, v12
	v_readlane_b32 s45, v247, 35
	s_nop 0
	v_addc_co_u32_e32 v15, vcc, 0, v13, vcc
	v_add_co_u32_e32 v16, vcc, s56, v12
	v_readlane_b32 s46, v247, 36
	s_nop 0
	v_addc_co_u32_e32 v17, vcc, 0, v13, vcc
	v_add_co_u32_e32 v18, vcc, s57, v12
	v_readlane_b32 s47, v247, 37
	s_nop 0
	v_addc_co_u32_e32 v19, vcc, 0, v13, vcc
	v_add_co_u32_e32 v20, vcc, s58, v12
	v_readlane_b32 s48, v247, 38
	s_nop 0
	v_addc_co_u32_e32 v21, vcc, 0, v13, vcc
	v_add_co_u32_e32 v22, vcc, s59, v12
	v_readlane_b32 s49, v247, 39
	s_nop 0
	v_addc_co_u32_e32 v23, vcc, 0, v13, vcc
	v_add_co_u32_e32 v24, vcc, s60, v12
	v_readlane_b32 s50, v247, 40
	s_nop 0
	v_addc_co_u32_e32 v25, vcc, 0, v13, vcc
	v_add_co_u32_e32 v26, vcc, s61, v12
	v_readlane_b32 s51, v247, 41
	s_nop 0
	v_addc_co_u32_e32 v27, vcc, 0, v13, vcc
	v_add_co_u32_e32 v28, vcc, s62, v12
	s_nop 1
	v_addc_co_u32_e32 v29, vcc, 0, v13, vcc
	global_load_dword v45, v[14:15], off nt
	global_load_dword v46, v[16:17], off nt
	global_load_dword v47, v[18:19], off nt
	global_load_dword v48, v[20:21], off nt
	global_load_dword v49, v[22:23], off nt
	global_load_dword v50, v[24:25], off nt
	global_load_dword v51, v[26:27], off nt
	global_load_dword v52, v[28:29], off nt
	v_add_co_u32_e32 v14, vcc, s63, v12
	s_nop 1
	v_addc_co_u32_e32 v15, vcc, 0, v13, vcc
	v_add_co_u32_e32 v16, vcc, s64, v12
	s_nop 1
	v_addc_co_u32_e32 v17, vcc, 0, v13, vcc
	v_add_co_u32_e32 v18, vcc, s65, v12
	s_nop 1
	v_addc_co_u32_e32 v19, vcc, 0, v13, vcc
	v_add_co_u32_e32 v20, vcc, s67, v12
	s_nop 1
	v_addc_co_u32_e32 v21, vcc, 0, v13, vcc
	v_add_co_u32_e32 v22, vcc, s68, v12
	s_nop 1
	v_addc_co_u32_e32 v23, vcc, 0, v13, vcc
	v_add_co_u32_e32 v24, vcc, s69, v12
	s_nop 1
	v_addc_co_u32_e32 v25, vcc, 0, v13, vcc
	v_add_co_u32_e32 v26, vcc, s70, v12
	s_nop 1
	v_addc_co_u32_e32 v27, vcc, 0, v13, vcc
	v_add_co_u32_e32 v28, vcc, s71, v12
	s_nop 1
	v_addc_co_u32_e32 v29, vcc, 0, v13, vcc
	global_load_dword v53, v[14:15], off nt
	global_load_dword v54, v[16:17], off nt
	global_load_dword v55, v[18:19], off nt
	global_load_dword v56, v[20:21], off nt
	global_load_dword v57, v[22:23], off nt
	global_load_dword v58, v[24:25], off nt
	global_load_dword v59, v[26:27], off nt
	s_nop 0
	global_load_dword v28, v[28:29], off nt
	v_add_co_u32_e32 v14, vcc, s72, v12
	s_nop 1
	v_addc_co_u32_e32 v15, vcc, 0, v13, vcc
	v_add_co_u32_e32 v16, vcc, s73, v12
	s_nop 1
	v_addc_co_u32_e32 v17, vcc, 0, v13, vcc
	v_add_co_u32_e32 v18, vcc, s74, v12
	s_nop 1
	v_addc_co_u32_e32 v19, vcc, 0, v13, vcc
	v_add_co_u32_e32 v20, vcc, s75, v12
	s_nop 1
	v_addc_co_u32_e32 v21, vcc, 0, v13, vcc
	v_add_co_u32_e32 v22, vcc, s76, v12
	s_nop 1
	v_addc_co_u32_e32 v23, vcc, 0, v13, vcc
	v_add_co_u32_e32 v24, vcc, s77, v12
	s_nop 1
	v_addc_co_u32_e32 v25, vcc, 0, v13, vcc
	v_add_co_u32_e32 v26, vcc, s78, v12
	s_nop 1
	v_addc_co_u32_e32 v27, vcc, 0, v13, vcc
	v_add_co_u32_e32 v12, vcc, s79, v12
	s_nop 1
	v_addc_co_u32_e32 v13, vcc, 0, v13, vcc
	global_load_dword v14, v[14:15], off nt
	s_nop 0
	global_load_dword v15, v[16:17], off nt
	s_nop 0
	global_load_dword v16, v[18:19], off nt
	global_load_dword v17, v[20:21], off nt
	s_nop 0
	global_load_dword v18, v[22:23], off nt
	global_load_dword v19, v[24:25], off nt
	global_load_dword v20, v[26:27], off nt
	s_nop 0
	global_load_dword v12, v[12:13], off nt
	s_waitcnt vmcnt(30)
	ds_write2_b32 v35, v31, v32 offset1:66
	s_waitcnt vmcnt(28)
	ds_write2_b32 v35, v33, v40 offset0:132 offset1:198
	s_waitcnt vmcnt(26)
	ds_write2_b32 v84, v41, v42 offset0:8 offset1:74
	s_waitcnt vmcnt(24)
	ds_write2_b32 v84, v43, v44 offset0:140 offset1:206
	s_waitcnt vmcnt(22)
	ds_write2_b32 v85, v45, v46 offset0:16 offset1:82
	s_waitcnt vmcnt(20)
	ds_write2_b32 v85, v47, v48 offset0:148 offset1:214
	s_waitcnt vmcnt(18)
	ds_write2_b32 v86, v49, v50 offset0:24 offset1:90
	s_waitcnt vmcnt(16)
	ds_write2_b32 v86, v51, v52 offset0:156 offset1:222
	s_waitcnt vmcnt(14)
	ds_write2_b32 v87, v53, v54 offset0:32 offset1:98
	s_waitcnt vmcnt(12)
	ds_write2_b32 v87, v55, v56 offset0:164 offset1:230
	s_waitcnt vmcnt(10)
	ds_write2_b32 v88, v57, v58 offset0:40 offset1:106
	s_waitcnt vmcnt(8)
	ds_write2_b32 v88, v59, v28 offset0:172 offset1:238
	s_waitcnt vmcnt(6)
	ds_write2_b32 v89, v14, v15 offset0:48 offset1:114
	s_waitcnt vmcnt(4)
	ds_write2_b32 v89, v16, v17 offset0:180 offset1:246
	s_waitcnt vmcnt(2)
	ds_write2_b32 v90, v18, v19 offset0:56 offset1:122
	s_waitcnt vmcnt(0)
	ds_write2_b32 v90, v20, v12 offset0:188 offset1:254
	s_waitcnt lgkmcnt(0)
	ds_read2_b32 v[12:13], v39 offset1:33
	v_lshlrev_b32_e32 v16, 1, v9
	v_mov_b32_e32 v17, v5
	s_waitcnt lgkmcnt(0)
	v_cvt_pk_bf16_f32 v12, v12, v13
	ds_read2_b32 v[14:15], v39 offset0:66 offset1:99
	v_lshl_add_u64 v[10:11], v[10:11], 0, v[16:17]
	v_mov_b32_e32 v9, v5
	s_waitcnt lgkmcnt(0)
	v_cvt_pk_bf16_f32 v13, v14, v15
	ds_read2_b32 v[14:15], v39 offset0:132 offset1:165
	v_lshl_add_u64 v[10:11], v[10:11], 0, v[8:9]
	v_or_b32_e32 v9, v30, v37
	s_waitcnt lgkmcnt(0)
	v_cvt_pk_bf16_f32 v14, v14, v15
	ds_read2_b32 v[18:19], v39 offset0:198 offset1:231
	v_mul_u32_u24_e32 v9, 0xb00, v9
	v_lshl_add_u64 v[16:17], v[10:11], 0, s[26:27]
	s_waitcnt lgkmcnt(0)
	v_cvt_pk_bf16_f32 v15, v18, v19
	v_lshlrev_b32_e32 v18, 1, v9
	v_mov_b32_e32 v19, v5
	ds_read2_b32 v[10:11], v39 offset0:8 offset1:41
	v_lshl_add_u64 v[18:19], v[16:17], 0, v[18:19]
	v_or_b32_e32 v9, v30, v77
	global_store_dwordx4 v[18:19], v[12:15], off nt
	s_waitcnt lgkmcnt(0)
	v_cvt_pk_bf16_f32 v10, v10, v11
	ds_read2_b32 v[12:13], v39 offset0:74 offset1:107
	v_mul_u32_u24_e32 v9, 0xb00, v9
	s_waitcnt lgkmcnt(0)
	v_cvt_pk_bf16_f32 v11, v12, v13
	ds_read2_b32 v[12:13], v39 offset0:140 offset1:173
	v_lshlrev_b32_e32 v18, 1, v9
	v_mov_b32_e32 v19, v5
	s_waitcnt lgkmcnt(0)
	v_cvt_pk_bf16_f32 v12, v12, v13
	ds_read2_b32 v[14:15], v39 offset0:206 offset1:239
	s_waitcnt lgkmcnt(0)
	v_cvt_pk_bf16_f32 v13, v14, v15
	v_lshl_add_u64 v[18:19], v[16:17], 0, v[18:19]
	v_or_b32_e32 v9, v30, v78
	ds_read2_b32 v[14:15], v39 offset0:16 offset1:49
	global_store_dwordx4 v[18:19], v[10:13], off nt
	v_mul_u32_u24_e32 v9, 0xb00, v9
	v_lshlrev_b32_e32 v18, 1, v9
	s_waitcnt lgkmcnt(0)
	v_cvt_pk_bf16_f32 v10, v14, v15
	ds_read2_b32 v[12:13], v39 offset0:82 offset1:115
	s_waitcnt lgkmcnt(0)
	v_cvt_pk_bf16_f32 v11, v12, v13
	ds_read2_b32 v[12:13], v39 offset0:148 offset1:181
	v_mov_b32_e32 v19, v5
	s_waitcnt lgkmcnt(0)
	v_cvt_pk_bf16_f32 v12, v12, v13
	ds_read2_b32 v[14:15], v39 offset0:214 offset1:247
	s_waitcnt lgkmcnt(0)
	v_cvt_pk_bf16_f32 v13, v14, v15
	v_lshl_add_u64 v[18:19], v[16:17], 0, v[18:19]
	ds_read2_b32 v[14:15], v39 offset0:24 offset1:57
	global_store_dwordx4 v[18:19], v[10:13], off nt
	v_or_b32_e32 v9, v30, v79
	v_mul_u32_u24_e32 v9, 0xb00, v9
	s_waitcnt lgkmcnt(0)
	v_cvt_pk_bf16_f32 v10, v14, v15
	ds_read2_b32 v[12:13], v39 offset0:90 offset1:123
	s_waitcnt lgkmcnt(0)
	v_cvt_pk_bf16_f32 v11, v12, v13
	ds_read2_b32 v[12:13], v39 offset0:156 offset1:189
	s_waitcnt lgkmcnt(0)
	v_cvt_pk_bf16_f32 v12, v12, v13
	ds_read2_b32 v[14:15], v39 offset0:222 offset1:255
	s_waitcnt lgkmcnt(0)
	v_cvt_pk_bf16_f32 v13, v14, v15
	v_lshlrev_b32_e32 v14, 1, v9
	v_mov_b32_e32 v15, v5
	v_lshl_add_u64 v[14:15], v[16:17], 0, v[14:15]
	global_store_dwordx4 v[14:15], v[10:13], off nt
	s_waitcnt lgkmcnt(0)

.LBB0_28:
	s_waitcnt vmcnt(30)
	ds_write2_b32 v35, v14, v15 offset1:66
	s_waitcnt vmcnt(28)
	ds_write2_b32 v35, v16, v17 offset0:132 offset1:198
	s_waitcnt vmcnt(26)
	ds_write2_b32 v84, v18, v19 offset0:8 offset1:74
	s_waitcnt vmcnt(24)
	ds_write2_b32 v84, v20, v21 offset0:140 offset1:206
	s_waitcnt vmcnt(22)
	ds_write2_b32 v85, v22, v23 offset0:16 offset1:82
	s_waitcnt vmcnt(20)
	ds_write2_b32 v85, v24, v25 offset0:148 offset1:214
	s_waitcnt vmcnt(18)
	ds_write2_b32 v86, v26, v27 offset0:24 offset1:90
	s_waitcnt vmcnt(16)
	ds_write2_b32 v86, v28, v29 offset0:156 offset1:222
	s_waitcnt vmcnt(14)
	ds_write2_b32 v87, v30, v31 offset0:32 offset1:98
	s_waitcnt vmcnt(12)
	ds_write2_b32 v87, v32, v33 offset0:164 offset1:230
	s_waitcnt vmcnt(10)
	ds_write2_b32 v88, v40, v41 offset0:40 offset1:106
	s_waitcnt vmcnt(8)
	ds_write2_b32 v88, v42, v43 offset0:172 offset1:238
	s_waitcnt vmcnt(6)
	ds_write2_b32 v89, v44, v45 offset0:48 offset1:114
	s_waitcnt vmcnt(4)
	ds_write2_b32 v89, v46, v47 offset0:180 offset1:246
	s_waitcnt vmcnt(2)
	ds_write2_b32 v90, v50, v51 offset0:56 offset1:122
	s_waitcnt vmcnt(0)
	ds_write2_b32 v90, v48, v49 offset0:188 offset1:254
	s_waitcnt lgkmcnt(0)
	v_lshlrev_b32_e32 v12, 5, v13
	s_movk_i32 s24, 0x57
	v_cmp_lt_u16_e32 vcc, s24, v13
	v_and_b32_e32 v14, 0x60, v12
	s_and_saveexec_b64 s[24:25], vcc
	s_xor_b64 s[24:25], exec, s[24:25]
	v_lshl_add_u32 v12, v13, 6, v91
	v_and_b32_e32 v12, 0x7fffff00, v12
	s_movk_i32 s26, 0x80
	v_or3_b32 v12, v14, v12, s26
	s_andn2_saveexec_b64 s[24:25], s[24:25]
	v_lshlrev_b16_e32 v12, 6, v13
	v_and_b32_e32 v12, 0x1f00, v12
	v_or_b32_sdwa v12, v14, v12 dst_sel:DWORD dst_unused:UNUSED_PAD src0_sel:DWORD src1_sel:WORD_0
	s_or_b64 exec, exec, s[24:25]
	v_lshlrev_b32_e32 v18, 1, v9
	v_mov_b32_e32 v19, v5
	ds_read2_b32 v[14:15], v39 offset1:33
	v_mov_b32_e32 v9, v5
	v_lshl_add_u64 v[10:11], v[10:11], 0, v[18:19]
	s_waitcnt lgkmcnt(0)
	v_cvt_pk_bf16_f32 v14, v14, v15
	ds_read2_b32 v[16:17], v39 offset0:66 offset1:99
	v_add_u32_e32 v20, v12, v37
	v_mov_b32_e32 v21, v5
	s_mov_b64 s[24:25], 0x500000
	v_lshl_add_u64 v[10:11], v[10:11], 0, v[8:9]
	s_waitcnt lgkmcnt(0)
	v_cvt_pk_bf16_f32 v15, v16, v17
	ds_read2_b32 v[16:17], v39 offset0:132 offset1:165
	v_lshlrev_b64 v[18:19], 11, v[20:21]
	v_lshl_add_u64 v[10:11], v[10:11], 0, s[24:25]
	s_waitcnt lgkmcnt(0)
	v_cvt_pk_bf16_f32 v16, v16, v17
	ds_read2_b32 v[22:23], v39 offset0:198 offset1:231
	s_waitcnt lgkmcnt(0)
	v_cvt_pk_bf16_f32 v17, v22, v23
	ds_read2_b32 v[20:21], v39 offset0:8 offset1:41
	v_lshl_add_u64 v[18:19], v[10:11], 0, v[18:19]
	global_store_dwordx4 v[18:19], v[14:17], off nt
	v_mov_b32_e32 v13, v5
	s_waitcnt lgkmcnt(0)
	v_cvt_pk_bf16_f32 v14, v20, v21
	ds_read2_b32 v[16:17], v39 offset0:74 offset1:107
	v_add_u32_e32 v20, v12, v77
	v_mov_b32_e32 v21, v5
	s_waitcnt lgkmcnt(0)
	v_cvt_pk_bf16_f32 v15, v16, v17
	ds_read2_b32 v[16:17], v39 offset0:140 offset1:173
	v_lshlrev_b64 v[20:21], 11, v[20:21]
	s_waitcnt lgkmcnt(0)
	v_cvt_pk_bf16_f32 v16, v16, v17
	ds_read2_b32 v[18:19], v39 offset0:206 offset1:239
	s_waitcnt lgkmcnt(0)
	v_cvt_pk_bf16_f32 v17, v18, v19
	v_lshl_add_u64 v[20:21], v[10:11], 0, v[20:21]
	ds_read2_b32 v[18:19], v39 offset0:16 offset1:49
	global_store_dwordx4 v[20:21], v[14:17], off nt
	v_add_u32_e32 v20, v12, v78
	v_mov_b32_e32 v21, v5
	s_waitcnt lgkmcnt(0)
	v_cvt_pk_bf16_f32 v14, v18, v19
	ds_read2_b32 v[16:17], v39 offset0:82 offset1:115
	s_waitcnt lgkmcnt(0)
	v_cvt_pk_bf16_f32 v15, v16, v17
	ds_read2_b32 v[16:17], v39 offset0:148 offset1:181
	v_lshlrev_b64 v[20:21], 11, v[20:21]
	s_waitcnt lgkmcnt(0)
	v_cvt_pk_bf16_f32 v16, v16, v17
	ds_read2_b32 v[18:19], v39 offset0:214 offset1:247
	s_waitcnt lgkmcnt(0)
	v_cvt_pk_bf16_f32 v17, v18, v19
	v_lshl_add_u64 v[20:21], v[10:11], 0, v[20:21]
	v_add_u32_e32 v12, v12, v79
	ds_read2_b32 v[18:19], v39 offset0:24 offset1:57
	global_store_dwordx4 v[20:21], v[14:17], off nt
	v_lshlrev_b64 v[12:13], 11, v[12:13]
	v_lshl_add_u64 v[10:11], v[10:11], 0, v[12:13]
	s_waitcnt lgkmcnt(0)
	v_cvt_pk_bf16_f32 v14, v18, v19
	ds_read2_b32 v[16:17], v39 offset0:90 offset1:123
	s_waitcnt lgkmcnt(0)
	v_cvt_pk_bf16_f32 v15, v16, v17
	ds_read2_b32 v[16:17], v39 offset0:156 offset1:189
	s_waitcnt lgkmcnt(0)
	v_cvt_pk_bf16_f32 v16, v16, v17
	ds_read2_b32 v[18:19], v39 offset0:222 offset1:255
	s_waitcnt lgkmcnt(0)
	v_cvt_pk_bf16_f32 v17, v18, v19
	global_store_dwordx4 v[10:11], v[14:17], off nt
	s_waitcnt lgkmcnt(0)

.LBB0_37:
	s_waitcnt vmcnt(30)
	ds_write2_b32 v35, v14, v15 offset1:66
	s_waitcnt vmcnt(28)
	ds_write2_b32 v35, v16, v17 offset0:132 offset1:198
	s_waitcnt vmcnt(26)
	ds_write2_b32 v84, v18, v19 offset0:8 offset1:74
	s_waitcnt vmcnt(24)
	ds_write2_b32 v84, v20, v21 offset0:140 offset1:206
	s_waitcnt vmcnt(22)
	ds_write2_b32 v85, v22, v23 offset0:16 offset1:82
	s_waitcnt vmcnt(20)
	ds_write2_b32 v85, v24, v25 offset0:148 offset1:214
	s_waitcnt vmcnt(18)
	ds_write2_b32 v86, v26, v27 offset0:24 offset1:90
	s_waitcnt vmcnt(16)
	ds_write2_b32 v86, v28, v29 offset0:156 offset1:222
	s_waitcnt vmcnt(14)
	ds_write2_b32 v87, v30, v31 offset0:32 offset1:98
	s_waitcnt vmcnt(12)
	ds_write2_b32 v87, v32, v33 offset0:164 offset1:230
	s_waitcnt vmcnt(10)
	ds_write2_b32 v88, v40, v41 offset0:40 offset1:106
	s_waitcnt vmcnt(8)
	ds_write2_b32 v88, v42, v43 offset0:172 offset1:238
	s_waitcnt vmcnt(6)
	ds_write2_b32 v89, v44, v45 offset0:48 offset1:114
	s_waitcnt vmcnt(4)
	ds_write2_b32 v89, v46, v47 offset0:180 offset1:246
	s_waitcnt vmcnt(2)
	ds_write2_b32 v90, v50, v51 offset0:56 offset1:122
	s_waitcnt vmcnt(0)
	ds_write2_b32 v90, v48, v49 offset0:188 offset1:254
	s_waitcnt lgkmcnt(0)
	ds_read2_b32 v[12:13], v39 offset1:33
	s_waitcnt lgkmcnt(0)
	v_cvt_pk_bf16_f32 v12, v12, v13
	ds_read2_b32 v[14:15], v39 offset0:66 offset1:99
	v_lshlrev_b32_e32 v16, 1, v9
	v_mov_b32_e32 v17, v5
	s_waitcnt lgkmcnt(0)
	v_cvt_pk_bf16_f32 v13, v14, v15
	ds_read2_b32 v[14:15], v39 offset0:132 offset1:165
	v_lshl_add_u64 v[10:11], v[10:11], 0, v[16:17]
	v_mov_b32_e32 v9, v5
	s_waitcnt lgkmcnt(0)
	v_cvt_pk_bf16_f32 v14, v14, v15
	ds_read2_b32 v[18:19], v39 offset0:198 offset1:231
	v_lshl_add_u64 v[10:11], v[10:11], 0, v[8:9]
	s_mov_b64 s[22:23], 0x300000
	v_or_b32_e32 v9, v152, v37
	v_lshl_add_u64 v[16:17], v[10:11], 0, s[22:23]
	s_waitcnt lgkmcnt(0)
	v_cvt_pk_bf16_f32 v15, v18, v19
	v_lshlrev_b32_e32 v18, 11, v9
	v_mov_b32_e32 v19, v5
	ds_read2_b32 v[10:11], v39 offset0:8 offset1:41
	v_lshl_add_u64 v[18:19], v[16:17], 0, v[18:19]
	global_store_dwordx4 v[18:19], v[12:15], off nt
	s_waitcnt lgkmcnt(0)
	v_cvt_pk_bf16_f32 v10, v10, v11
	ds_read2_b32 v[12:13], v39 offset0:74 offset1:107
	v_or_b32_e32 v9, v152, v77
	s_waitcnt lgkmcnt(0)
	v_cvt_pk_bf16_f32 v11, v12, v13
	ds_read2_b32 v[12:13], v39 offset0:140 offset1:173
	v_lshlrev_b32_e32 v18, 11, v9
	v_mov_b32_e32 v19, v5
	s_waitcnt lgkmcnt(0)
	v_cvt_pk_bf16_f32 v12, v12, v13
	ds_read2_b32 v[14:15], v39 offset0:206 offset1:239
	s_waitcnt lgkmcnt(0)
	v_cvt_pk_bf16_f32 v13, v14, v15
	v_lshl_add_u64 v[18:19], v[16:17], 0, v[18:19]
	ds_read2_b32 v[14:15], v39 offset0:16 offset1:49
	global_store_dwordx4 v[18:19], v[10:13], off nt
	v_or_b32_e32 v9, v152, v78
	v_mov_b32_e32 v19, v5
	s_waitcnt lgkmcnt(0)
	v_cvt_pk_bf16_f32 v10, v14, v15
	ds_read2_b32 v[12:13], v39 offset0:82 offset1:115
	s_waitcnt lgkmcnt(0)
	v_cvt_pk_bf16_f32 v11, v12, v13
	ds_read2_b32 v[12:13], v39 offset0:148 offset1:181
	v_lshlrev_b32_e32 v18, 11, v9
	s_waitcnt lgkmcnt(0)
	v_cvt_pk_bf16_f32 v12, v12, v13
	ds_read2_b32 v[14:15], v39 offset0:214 offset1:247
	s_waitcnt lgkmcnt(0)
	v_cvt_pk_bf16_f32 v13, v14, v15
	v_lshl_add_u64 v[18:19], v[16:17], 0, v[18:19]
	ds_read2_b32 v[14:15], v39 offset0:24 offset1:57
	global_store_dwordx4 v[18:19], v[10:13], off nt
	v_or_b32_e32 v9, v152, v79
	v_mov_b32_e32 v19, v5
	s_waitcnt lgkmcnt(0)
	v_cvt_pk_bf16_f32 v10, v14, v15
	ds_read2_b32 v[12:13], v39 offset0:90 offset1:123
	s_waitcnt lgkmcnt(0)
	v_cvt_pk_bf16_f32 v11, v12, v13
	ds_read2_b32 v[12:13], v39 offset0:156 offset1:189
	s_waitcnt lgkmcnt(0)
	v_cvt_pk_bf16_f32 v12, v12, v13
	ds_read2_b32 v[14:15], v39 offset0:222 offset1:255
	v_lshlrev_b32_e32 v18, 11, v9
	s_waitcnt lgkmcnt(0)
	v_cvt_pk_bf16_f32 v13, v14, v15
	v_lshl_add_u64 v[14:15], v[16:17], 0, v[18:19]
	global_store_dwordx4 v[14:15], v[10:13], off nt
	s_waitcnt lgkmcnt(0)

.LBB0_39:
	s_andn2_saveexec_b64 s[18:19], s[18:19]
	s_cbranch_execz .LBB0_41
	v_lshlrev_b32_e32 v9, 2, v14
	v_lshlrev_b32_e32 v14, 5, v14
	v_readlane_b32 s36, v247, 6
	v_sub_u32_e32 v9, v81, v9
	v_sub_u32_e32 v14, v80, v14
	v_lshlrev_b64 v[12:13], 20, v[12:13]
	v_readlane_b32 s44, v247, 14
	v_readlane_b32 s45, v247, 15
	v_and_b32_e32 v15, 0x3c0, v9
	v_and_b32_e32 v22, 0x1e0, v14
	v_lshl_add_u64 v[12:13], s[44:45], 0, v[12:13]
	v_bitop3_b32 v16, v15, v3, s81 bitop3:0xde
	v_lshlrev_b32_e32 v14, 2, v22
	v_mov_b32_e32 v15, v5
	v_lshl_add_u64 v[12:13], v[12:13], 0, v[14:15]
	v_lshl_add_u64 v[12:13], v[12:13], 0, v[4:5]
	v_lshlrev_b32_e32 v14, 11, v16
	v_lshl_add_u64 v[12:13], v[12:13], 0, v[14:15]
	v_add_co_u32_e32 v14, vcc, s31, v12
	s_mov_b32 s20, 0x1f000
	s_nop 0
	v_addc_co_u32_e32 v15, vcc, 0, v13, vcc
	v_add_co_u32_e32 v16, vcc, s34, v12
	v_bitop3_b32 v9, v9, s81, v92 bitop3:0x6c
	s_nop 0
	v_addc_co_u32_e32 v17, vcc, 0, v13, vcc
	v_add_co_u32_e32 v18, vcc, s3, v12
	v_readlane_b32 s37, v247, 7
	s_nop 0
	v_addc_co_u32_e32 v19, vcc, 0, v13, vcc
	global_load_dword v23, v[12:13], off nt
	global_load_dword v24, v[14:15], off offset:-4096 nt
	global_load_dword v25, v[14:15], off nt
	global_load_dword v26, v[16:17], off offset:-4096 nt
	global_load_dword v27, v[16:17], off nt
	global_load_dword v28, v[18:19], off offset:-4096 nt
	global_load_dword v29, v[18:19], off nt
	v_add_co_u32_e32 v14, vcc, s35, v12
	v_readlane_b32 s38, v247, 8
	s_nop 0
	v_addc_co_u32_e32 v15, vcc, 0, v13, vcc
	v_add_co_u32_e32 v16, vcc, s52, v12
	v_readlane_b32 s39, v247, 9
	s_nop 0
	v_addc_co_u32_e32 v17, vcc, 0, v13, vcc
	v_add_co_u32_e32 v18, vcc, s53, v12
	v_readlane_b32 s40, v247, 10
	s_nop 0
	v_addc_co_u32_e32 v19, vcc, 0, v13, vcc
	v_add_co_u32_e32 v20, vcc, s54, v12
	v_readlane_b32 s41, v247, 11
	s_nop 0
	v_addc_co_u32_e32 v21, vcc, 0, v13, vcc
	global_load_dword v30, v[14:15], off offset:-4096 nt
	global_load_dword v31, v[14:15], off nt
	global_load_dword v32, v[16:17], off offset:-4096 nt
	global_load_dword v33, v[16:17], off nt
	global_load_dword v40, v[18:19], off offset:-4096 nt
	global_load_dword v41, v[18:19], off nt
	global_load_dword v42, v[20:21], off offset:-4096 nt
	global_load_dword v43, v[20:21], off nt
	v_add_co_u32_e32 v14, vcc, s55, v12
	v_readlane_b32 s42, v247, 12
	s_nop 0
	v_addc_co_u32_e32 v15, vcc, 0, v13, vcc
	v_add_co_u32_e32 v16, vcc, s56, v12
	v_readlane_b32 s43, v247, 13
	s_nop 0
	v_addc_co_u32_e32 v17, vcc, 0, v13, vcc
	v_add_co_u32_e32 v18, vcc, s57, v12
	v_readlane_b32 s46, v247, 16
	s_nop 0
	v_addc_co_u32_e32 v19, vcc, 0, v13, vcc
	v_add_co_u32_e32 v20, vcc, s58, v12
	v_readlane_b32 s47, v247, 17
	s_nop 0
	v_addc_co_u32_e32 v21, vcc, 0, v13, vcc
	global_load_dword v44, v[14:15], off offset:-4096 nt
	global_load_dword v45, v[14:15], off nt
	global_load_dword v46, v[16:17], off offset:-4096 nt
	global_load_dword v47, v[16:17], off nt
	global_load_dword v48, v[18:19], off offset:-4096 nt
	global_load_dword v49, v[18:19], off nt
	global_load_dword v50, v[20:21], off offset:-4096 nt
	global_load_dword v51, v[20:21], off nt
	v_add_co_u32_e32 v14, vcc, s59, v12
	v_readlane_b32 s48, v247, 18
	s_nop 0
	v_addc_co_u32_e32 v15, vcc, 0, v13, vcc
	v_add_co_u32_e32 v16, vcc, s60, v12
	v_readlane_b32 s49, v247, 19
	s_nop 0
	v_addc_co_u32_e32 v17, vcc, 0, v13, vcc
	v_add_co_u32_e32 v18, vcc, s61, v12
	v_readlane_b32 s50, v247, 20
	s_nop 0
	v_addc_co_u32_e32 v19, vcc, 0, v13, vcc
	v_add_co_u32_e32 v20, vcc, s62, v12
	v_readlane_b32 s51, v247, 21
	s_nop 0
	v_addc_co_u32_e32 v21, vcc, 0, v13, vcc
	global_load_dword v52, v[14:15], off offset:-4096 nt
	s_nop 0
	global_load_dword v14, v[14:15], off nt
	s_nop 0
	global_load_dword v15, v[16:17], off offset:-4096 nt
	s_nop 0
	global_load_dword v16, v[16:17], off nt
	s_nop 0
	global_load_dword v17, v[18:19], off offset:-4096 nt
	s_nop 0
	global_load_dword v18, v[18:19], off nt
	s_nop 0
	global_load_dword v19, v[20:21], off offset:-4096 nt
	s_nop 0
	global_load_dword v20, v[20:21], off nt
	v_add_co_u32_e32 v12, vcc, s20, v12
	s_mov_b64 s[20:21], 0x280000
	s_nop 0
	v_addc_co_u32_e32 v13, vcc, 0, v13, vcc
	global_load_dword v12, v[12:13], off nt
	s_waitcnt vmcnt(30)
	ds_write2_b32 v35, v23, v24 offset1:66
	s_waitcnt vmcnt(28)
	ds_write2_b32 v35, v25, v26 offset0:132 offset1:198
	s_waitcnt vmcnt(26)
	ds_write2_b32 v84, v27, v28 offset0:8 offset1:74
	s_waitcnt vmcnt(24)
	ds_write2_b32 v84, v29, v30 offset0:140 offset1:206
	s_waitcnt vmcnt(22)
	ds_write2_b32 v85, v31, v32 offset0:16 offset1:82
	s_waitcnt vmcnt(20)
	ds_write2_b32 v85, v33, v40 offset0:148 offset1:214
	s_waitcnt vmcnt(18)
	ds_write2_b32 v86, v41, v42 offset0:24 offset1:90
	s_waitcnt vmcnt(16)
	ds_write2_b32 v86, v43, v44 offset0:156 offset1:222
	s_waitcnt vmcnt(14)
	ds_write2_b32 v87, v45, v46 offset0:32 offset1:98
	s_waitcnt vmcnt(12)
	ds_write2_b32 v87, v47, v48 offset0:164 offset1:230
	s_waitcnt vmcnt(10)
	ds_write2_b32 v88, v49, v50 offset0:40 offset1:106
	s_waitcnt vmcnt(8)
	ds_write2_b32 v88, v51, v52 offset0:172 offset1:238
	s_waitcnt vmcnt(6)
	ds_write2_b32 v89, v14, v15 offset0:48 offset1:114
	s_waitcnt vmcnt(4)
	ds_write2_b32 v89, v16, v17 offset0:180 offset1:246
	s_waitcnt vmcnt(2)
	ds_write2_b32 v90, v18, v19 offset0:56 offset1:122
	s_waitcnt vmcnt(0)
	ds_write2_b32 v90, v20, v12 offset0:188 offset1:254
	s_waitcnt lgkmcnt(0)
	ds_read2_b32 v[12:13], v39 offset1:33
	s_waitcnt lgkmcnt(0)
	v_cvt_pk_bf16_f32 v12, v12, v13
	ds_read2_b32 v[14:15], v39 offset0:66 offset1:99
	v_lshlrev_b32_e32 v16, 1, v9
	v_mov_b32_e32 v17, v5
	s_waitcnt lgkmcnt(0)
	v_cvt_pk_bf16_f32 v13, v14, v15
	ds_read2_b32 v[14:15], v39 offset0:132 offset1:165
	v_lshl_add_u64 v[10:11], v[10:11], 0, v[16:17]
	v_mov_b32_e32 v9, v5
	s_waitcnt lgkmcnt(0)
	v_cvt_pk_bf16_f32 v14, v14, v15
	ds_read2_b32 v[18:19], v39 offset0:198 offset1:231
	v_lshl_add_u64 v[10:11], v[10:11], 0, v[8:9]
	v_or_b32_e32 v9, v22, v37
	v_lshl_add_u64 v[16:17], v[10:11], 0, s[20:21]
	s_waitcnt lgkmcnt(0)
	v_cvt_pk_bf16_f32 v15, v18, v19
	v_lshlrev_b32_e32 v18, 10, v9
	v_mov_b32_e32 v19, v5
	ds_read2_b32 v[10:11], v39 offset0:8 offset1:41
	v_lshl_add_u64 v[18:19], v[16:17], 0, v[18:19]
	global_store_dwordx4 v[18:19], v[12:15], off nt
	s_waitcnt lgkmcnt(0)
	v_cvt_pk_bf16_f32 v10, v10, v11
	ds_read2_b32 v[12:13], v39 offset0:74 offset1:107
	v_or_b32_e32 v9, v22, v77
	s_waitcnt lgkmcnt(0)
	v_cvt_pk_bf16_f32 v11, v12, v13
	ds_read2_b32 v[12:13], v39 offset0:140 offset1:173
	v_lshlrev_b32_e32 v18, 10, v9
	v_mov_b32_e32 v19, v5
	s_waitcnt lgkmcnt(0)
	v_cvt_pk_bf16_f32 v12, v12, v13
	ds_read2_b32 v[14:15], v39 offset0:206 offset1:239
	s_waitcnt lgkmcnt(0)
	v_cvt_pk_bf16_f32 v13, v14, v15
	v_lshl_add_u64 v[18:19], v[16:17], 0, v[18:19]
	ds_read2_b32 v[14:15], v39 offset0:16 offset1:49
	global_store_dwordx4 v[18:19], v[10:13], off nt
	v_or_b32_e32 v9, v22, v78
	v_lshlrev_b32_e32 v18, 10, v9
	s_waitcnt lgkmcnt(0)
	v_cvt_pk_bf16_f32 v10, v14, v15
	ds_read2_b32 v[12:13], v39 offset0:82 offset1:115
	s_waitcnt lgkmcnt(0)
	v_cvt_pk_bf16_f32 v11, v12, v13
	ds_read2_b32 v[12:13], v39 offset0:148 offset1:181
	v_mov_b32_e32 v19, v5
	s_waitcnt lgkmcnt(0)
	v_cvt_pk_bf16_f32 v12, v12, v13
	ds_read2_b32 v[14:15], v39 offset0:214 offset1:247
	s_waitcnt lgkmcnt(0)
	v_cvt_pk_bf16_f32 v13, v14, v15
	v_lshl_add_u64 v[18:19], v[16:17], 0, v[18:19]
	ds_read2_b32 v[14:15], v39 offset0:24 offset1:57
	global_store_dwordx4 v[18:19], v[10:13], off nt
	v_or_b32_e32 v9, v22, v79
	s_waitcnt lgkmcnt(0)
	v_cvt_pk_bf16_f32 v10, v14, v15
	ds_read2_b32 v[12:13], v39 offset0:90 offset1:123
	s_waitcnt lgkmcnt(0)
	v_cvt_pk_bf16_f32 v11, v12, v13
	ds_read2_b32 v[12:13], v39 offset0:156 offset1:189
	s_waitcnt lgkmcnt(0)
	v_cvt_pk_bf16_f32 v12, v12, v13
	ds_read2_b32 v[14:15], v39 offset0:222 offset1:255
	s_waitcnt lgkmcnt(0)
	v_cvt_pk_bf16_f32 v13, v14, v15
	v_lshlrev_b32_e32 v14, 10, v9
	v_mov_b32_e32 v15, v5
	v_lshl_add_u64 v[14:15], v[16:17], 0, v[14:15]
	global_store_dwordx4 v[14:15], v[10:13], off nt
	s_waitcnt lgkmcnt(0)

.LBB0_61:
	v_ashrrev_i32_e32 v7, 31, v6
	v_lshl_add_u64 v[18:19], v[6:7], 4, s[18:19]
	global_load_dwordx4 v[10:13], v[18:19], off nt
	global_load_dwordx4 v[14:17], v[18:19], off offset:16 nt
	v_add_u32_e32 v1, s0, v1
	v_cmp_lt_i32_e32 vcc, s3, v1
	v_add_u32_e32 v6, s1, v6
	s_or_b64 s[10:11], vcc, s[10:11]
	s_waitcnt vmcnt(1)
	v_cvt_pk_bf16_f32 v10, v10, v11
	v_cvt_pk_bf16_f32 v11, v12, v13
	s_waitcnt vmcnt(0)
	v_cvt_pk_bf16_f32 v12, v14, v15
	v_cvt_pk_bf16_f32 v13, v16, v17
	global_store_dwordx4 v[4:5], v[10:13], off nt
	v_lshl_add_u64 v[4:5], v[4:5], 0, s[6:7]
	s_andn2_b64 exec, exec, s[10:11]
	s_cbranch_execnz .LBB0_61

.LBB0_65:
	v_cmp_lt_i32_e32 vcc, s1, v2
	s_and_saveexec_b64 s[10:11], vcc
	s_cbranch_execz .LBB0_64
	v_lshl_add_u64 v[10:11], v[2:3], 4, s[8:9]
	global_store_dwordx4 v[10:11], v[4:7], off nt
	s_branch .LBB0_64

.LBB0_69:
	s_or_b64 exec, exec, s[68:69]
	v_lshl_add_u64 v[2:3], v[2:3], 0, v[72:73]
	s_waitcnt lgkmcnt(0)
	v_cvt_pk_bf16_f32 v4, v5, v4
	v_cvt_pk_bf16_f32 v5, v7, v6
	v_cvt_pk_bf16_f32 v6, v9, v8
	v_cvt_pk_bf16_f32 v7, v11, v10
	global_store_dwordx4 v[2:3], v[4:7], off nt

.LBB0_79:
	s_or_b64 exec, exec, s[74:75]
	ds_read_b64 v[2:3], v85 offset:512
	ds_read_b64 v[4:5], v86 offset:16896
	v_mov_b32_e32 v81, v21
	v_lshlrev_b32_e32 v20, 1, v22
	s_mov_b64 s[74:75], 0
	s_waitcnt lgkmcnt(0)
	v_pk_mul_f32 v[6:7], v[2:3], v[4:5]
	v_pk_mul_f32 v[2:3], v[2:3], v[4:5] op_sel:[1,0] op_sel_hi:[0,1]
	v_add_f32_e32 v2, v2, v3
	v_sub_f32_e32 v4, v6, v7
	v_xor_b32_e32 v2, 0x80000000, v2
	v_cvt_pk_bf16_f32 v4, v4, v2
	ds_read_b64 v[2:3], v85 offset:520
	ds_read_b64 v[6:7], v86 offset:16904
	s_waitcnt lgkmcnt(0)
	v_pk_mul_f32 v[8:9], v[2:3], v[6:7]
	v_pk_mul_f32 v[2:3], v[2:3], v[6:7] op_sel:[1,0] op_sel_hi:[0,1]
	v_add_f32_e32 v2, v2, v3
	v_sub_f32_e32 v5, v8, v9
	v_xor_b32_e32 v2, 0x80000000, v2
	v_cvt_pk_bf16_f32 v5, v5, v2
	ds_read_b64 v[2:3], v85 offset:528
	ds_read_b64 v[6:7], v86 offset:16912
	s_waitcnt lgkmcnt(0)
	v_pk_mul_f32 v[8:9], v[2:3], v[6:7]
	v_pk_mul_f32 v[2:3], v[2:3], v[6:7] op_sel:[1,0] op_sel_hi:[0,1]
	v_add_f32_e32 v2, v2, v3
	v_sub_f32_e32 v6, v8, v9
	v_xor_b32_e32 v2, 0x80000000, v2
	v_cvt_pk_bf16_f32 v6, v6, v2
	ds_read_b64 v[2:3], v85 offset:536
	ds_read_b64 v[8:9], v86 offset:16920
	s_waitcnt lgkmcnt(0)
	v_pk_mul_f32 v[10:11], v[2:3], v[8:9]
	v_pk_mul_f32 v[2:3], v[2:3], v[8:9] op_sel:[1,0] op_sel_hi:[0,1]
	v_sub_f32_e32 v7, v10, v11
	v_add_f32_e32 v2, v2, v3
	v_xor_b32_e32 v2, 0x80000000, v2
	v_cvt_pk_bf16_f32 v7, v7, v2
	ds_read_b64 v[8:9], v88 offset:512
	ds_read_b64 v[10:11], v89 offset:16896
	v_lshl_add_u64 v[2:3], s[82:83], 0, v[80:81]
	v_lshl_add_u64 v[2:3], v[2:3], 0, s[72:73]
	v_lshl_add_u64 v[12:13], v[2:3], 0, v[24:25]
	global_store_dwordx4 v[12:13], v[4:7], off nt
	s_waitcnt lgkmcnt(0)
	s_nop 0
	v_pk_mul_f32 v[4:5], v[8:9], v[10:11]
	s_nop 0
	v_sub_f32_e32 v6, v4, v5
	v_pk_mul_f32 v[4:5], v[8:9], v[10:11] op_sel:[1,0] op_sel_hi:[0,1]
	v_add_f32_e32 v4, v4, v5
	v_xor_b32_e32 v4, 0x80000000, v4
	v_cvt_pk_bf16_f32 v4, v6, v4
	ds_read_b64 v[6:7], v88 offset:520
	ds_read_b64 v[8:9], v89 offset:16904
	s_waitcnt lgkmcnt(0)
	v_pk_mul_f32 v[10:11], v[6:7], v[8:9]
	v_pk_mul_f32 v[6:7], v[6:7], v[8:9] op_sel:[1,0] op_sel_hi:[0,1]
	v_add_f32_e32 v6, v6, v7
	v_sub_f32_e32 v5, v10, v11
	v_xor_b32_e32 v6, 0x80000000, v6
	v_cvt_pk_bf16_f32 v5, v5, v6
	ds_read_b64 v[6:7], v88 offset:528
	ds_read_b64 v[8:9], v89 offset:16912
	s_waitcnt lgkmcnt(0)
	v_pk_mul_f32 v[10:11], v[6:7], v[8:9]
	v_pk_mul_f32 v[6:7], v[6:7], v[8:9] op_sel:[1,0] op_sel_hi:[0,1]
	v_add_f32_e32 v6, v6, v7
	v_sub_f32_e32 v10, v10, v11
	v_xor_b32_e32 v6, 0x80000000, v6
	v_cvt_pk_bf16_f32 v6, v10, v6
	ds_read_b64 v[8:9], v88 offset:536
	ds_read_b64 v[10:11], v89 offset:16920
	s_waitcnt lgkmcnt(0)
	v_pk_mul_f32 v[12:13], v[8:9], v[10:11]
	v_pk_mul_f32 v[8:9], v[8:9], v[10:11] op_sel:[1,0] op_sel_hi:[0,1]
	v_add_f32_e32 v8, v8, v9
	v_sub_f32_e32 v7, v12, v13
	v_xor_b32_e32 v8, 0x80000000, v8
	v_cvt_pk_bf16_f32 v7, v7, v8
	ds_read_b64 v[8:9], v91 offset:512
	ds_read_b64 v[10:11], v92 offset:16896
	v_lshl_add_u64 v[12:13], v[2:3], 0, v[26:27]
	global_store_dwordx4 v[12:13], v[4:7], off nt
	s_waitcnt lgkmcnt(0)
	s_nop 0
	v_pk_mul_f32 v[4:5], v[8:9], v[10:11]
	s_nop 0
	v_sub_f32_e32 v6, v4, v5
	v_pk_mul_f32 v[4:5], v[8:9], v[10:11] op_sel:[1,0] op_sel_hi:[0,1]
	v_add_f32_e32 v4, v4, v5
	v_xor_b32_e32 v4, 0x80000000, v4
	v_cvt_pk_bf16_f32 v4, v6, v4
	ds_read_b64 v[6:7], v91 offset:520
	ds_read_b64 v[8:9], v92 offset:16904
	s_waitcnt lgkmcnt(0)
	v_pk_mul_f32 v[10:11], v[6:7], v[8:9]
	v_pk_mul_f32 v[6:7], v[6:7], v[8:9] op_sel:[1,0] op_sel_hi:[0,1]
	v_add_f32_e32 v6, v6, v7
	v_sub_f32_e32 v5, v10, v11
	v_xor_b32_e32 v6, 0x80000000, v6
	v_cvt_pk_bf16_f32 v5, v5, v6
	ds_read_b64 v[6:7], v91 offset:528
	ds_read_b64 v[8:9], v92 offset:16912
	s_waitcnt lgkmcnt(0)
	v_pk_mul_f32 v[10:11], v[6:7], v[8:9]
	v_pk_mul_f32 v[6:7], v[6:7], v[8:9] op_sel:[1,0] op_sel_hi:[0,1]
	v_add_f32_e32 v6, v6, v7
	v_sub_f32_e32 v10, v10, v11
	v_xor_b32_e32 v6, 0x80000000, v6
	v_cvt_pk_bf16_f32 v6, v10, v6
	ds_read_b64 v[8:9], v91 offset:536
	ds_read_b64 v[10:11], v92 offset:16920
	s_waitcnt lgkmcnt(0)
	v_pk_mul_f32 v[12:13], v[8:9], v[10:11]
	v_pk_mul_f32 v[8:9], v[8:9], v[10:11] op_sel:[1,0] op_sel_hi:[0,1]
	v_add_f32_e32 v8, v8, v9
	v_sub_f32_e32 v7, v12, v13
	v_xor_b32_e32 v8, 0x80000000, v8
	v_cvt_pk_bf16_f32 v7, v7, v8
	ds_read_b64 v[8:9], v94 offset:512
	ds_read_b64 v[10:11], v95 offset:16896
	v_lshl_add_u64 v[12:13], v[2:3], 0, v[28:29]
	global_store_dwordx4 v[12:13], v[4:7], off nt
	s_waitcnt lgkmcnt(0)
	s_nop 0
	v_pk_mul_f32 v[4:5], v[8:9], v[10:11]
	s_nop 0
	v_sub_f32_e32 v6, v4, v5
	v_pk_mul_f32 v[4:5], v[8:9], v[10:11] op_sel:[1,0] op_sel_hi:[0,1]
	v_add_f32_e32 v4, v4, v5
	v_xor_b32_e32 v4, 0x80000000, v4
	v_cvt_pk_bf16_f32 v4, v6, v4
	ds_read_b64 v[6:7], v94 offset:520
	ds_read_b64 v[8:9], v95 offset:16904
	s_waitcnt lgkmcnt(0)
	v_pk_mul_f32 v[10:11], v[6:7], v[8:9]
	v_pk_mul_f32 v[6:7], v[6:7], v[8:9] op_sel:[1,0] op_sel_hi:[0,1]
	v_add_f32_e32 v6, v6, v7
	v_sub_f32_e32 v5, v10, v11
	v_xor_b32_e32 v6, 0x80000000, v6
	v_cvt_pk_bf16_f32 v5, v5, v6
	ds_read_b64 v[6:7], v94 offset:528
	ds_read_b64 v[8:9], v95 offset:16912
	s_waitcnt lgkmcnt(0)
	v_pk_mul_f32 v[10:11], v[6:7], v[8:9]
	v_pk_mul_f32 v[6:7], v[6:7], v[8:9] op_sel:[1,0] op_sel_hi:[0,1]
	v_add_f32_e32 v6, v6, v7
	v_sub_f32_e32 v10, v10, v11
	v_xor_b32_e32 v6, 0x80000000, v6
	v_cvt_pk_bf16_f32 v6, v10, v6
	ds_read_b64 v[8:9], v94 offset:536
	ds_read_b64 v[10:11], v95 offset:16920
	s_waitcnt lgkmcnt(0)
	v_pk_mul_f32 v[12:13], v[8:9], v[10:11]
	v_pk_mul_f32 v[8:9], v[8:9], v[10:11] op_sel:[1,0] op_sel_hi:[0,1]
	v_add_f32_e32 v8, v8, v9
	v_sub_f32_e32 v7, v12, v13
	v_xor_b32_e32 v8, 0x80000000, v8
	v_cvt_pk_bf16_f32 v7, v7, v8
	ds_read_b64 v[8:9], v97 offset:512
	ds_read_b64 v[10:11], v98 offset:16896
	v_lshl_add_u64 v[12:13], v[2:3], 0, v[30:31]
	global_store_dwordx4 v[12:13], v[4:7], off nt
	s_waitcnt lgkmcnt(0)
	s_nop 0
	v_pk_mul_f32 v[4:5], v[8:9], v[10:11]
	s_nop 0
	v_sub_f32_e32 v6, v4, v5
	v_pk_mul_f32 v[4:5], v[8:9], v[10:11] op_sel:[1,0] op_sel_hi:[0,1]
	v_add_f32_e32 v4, v4, v5
	v_xor_b32_e32 v4, 0x80000000, v4
	v_cvt_pk_bf16_f32 v4, v6, v4
	ds_read_b64 v[6:7], v97 offset:520
	ds_read_b64 v[8:9], v98 offset:16904
	s_waitcnt lgkmcnt(0)
	v_pk_mul_f32 v[10:11], v[6:7], v[8:9]
	v_pk_mul_f32 v[6:7], v[6:7], v[8:9] op_sel:[1,0] op_sel_hi:[0,1]
	v_add_f32_e32 v6, v6, v7
	v_sub_f32_e32 v5, v10, v11
	v_xor_b32_e32 v6, 0x80000000, v6
	v_cvt_pk_bf16_f32 v5, v5, v6
	ds_read_b64 v[6:7], v97 offset:528
	ds_read_b64 v[8:9], v98 offset:16912
	s_waitcnt lgkmcnt(0)
	v_pk_mul_f32 v[10:11], v[6:7], v[8:9]
	v_pk_mul_f32 v[6:7], v[6:7], v[8:9] op_sel:[1,0] op_sel_hi:[0,1]
	v_add_f32_e32 v6, v6, v7
	v_sub_f32_e32 v10, v10, v11
	v_xor_b32_e32 v6, 0x80000000, v6
	v_cvt_pk_bf16_f32 v6, v10, v6
	ds_read_b64 v[8:9], v97 offset:536
	ds_read_b64 v[10:11], v98 offset:16920
	s_waitcnt lgkmcnt(0)
	v_pk_mul_f32 v[12:13], v[8:9], v[10:11]
	v_pk_mul_f32 v[8:9], v[8:9], v[10:11] op_sel:[1,0] op_sel_hi:[0,1]
	v_add_f32_e32 v8, v8, v9
	v_sub_f32_e32 v7, v12, v13
	v_xor_b32_e32 v8, 0x80000000, v8
	v_cvt_pk_bf16_f32 v7, v7, v8
	ds_read_b64 v[8:9], v100 offset:512
	ds_read_b64 v[10:11], v101 offset:16896
	v_lshl_add_u64 v[12:13], v[2:3], 0, v[32:33]
	global_store_dwordx4 v[12:13], v[4:7], off nt
	s_waitcnt lgkmcnt(0)
	s_nop 0
	v_pk_mul_f32 v[4:5], v[8:9], v[10:11]
	s_nop 0
	v_sub_f32_e32 v6, v4, v5
	v_pk_mul_f32 v[4:5], v[8:9], v[10:11] op_sel:[1,0] op_sel_hi:[0,1]
	v_add_f32_e32 v4, v4, v5
	v_xor_b32_e32 v4, 0x80000000, v4
	v_cvt_pk_bf16_f32 v4, v6, v4
	ds_read_b64 v[6:7], v100 offset:520
	ds_read_b64 v[8:9], v101 offset:16904
	s_waitcnt lgkmcnt(0)
	v_pk_mul_f32 v[10:11], v[6:7], v[8:9]
	v_pk_mul_f32 v[6:7], v[6:7], v[8:9] op_sel:[1,0] op_sel_hi:[0,1]
	v_add_f32_e32 v6, v6, v7
	v_sub_f32_e32 v5, v10, v11
	v_xor_b32_e32 v6, 0x80000000, v6
	v_cvt_pk_bf16_f32 v5, v5, v6
	ds_read_b64 v[6:7], v100 offset:528
	ds_read_b64 v[8:9], v101 offset:16912
	s_waitcnt lgkmcnt(0)
	v_pk_mul_f32 v[10:11], v[6:7], v[8:9]
	v_pk_mul_f32 v[6:7], v[6:7], v[8:9] op_sel:[1,0] op_sel_hi:[0,1]
	v_add_f32_e32 v6, v6, v7
	v_sub_f32_e32 v10, v10, v11
	v_xor_b32_e32 v6, 0x80000000, v6
	v_cvt_pk_bf16_f32 v6, v10, v6
	ds_read_b64 v[8:9], v100 offset:536
	ds_read_b64 v[10:11], v101 offset:16920
	s_waitcnt lgkmcnt(0)
	v_pk_mul_f32 v[12:13], v[8:9], v[10:11]
	v_pk_mul_f32 v[8:9], v[8:9], v[10:11] op_sel:[1,0] op_sel_hi:[0,1]
	v_add_f32_e32 v8, v8, v9
	v_sub_f32_e32 v7, v12, v13
	v_xor_b32_e32 v8, 0x80000000, v8
	v_cvt_pk_bf16_f32 v7, v7, v8
	ds_read_b64 v[8:9], v103 offset:512
	ds_read_b64 v[10:11], v104 offset:16896
	v_lshl_add_u64 v[12:13], v[2:3], 0, v[36:37]
	global_store_dwordx4 v[12:13], v[4:7], off nt
	s_waitcnt lgkmcnt(0)
	s_nop 0
	v_pk_mul_f32 v[4:5], v[8:9], v[10:11]
	s_nop 0
	v_sub_f32_e32 v6, v4, v5
	v_pk_mul_f32 v[4:5], v[8:9], v[10:11] op_sel:[1,0] op_sel_hi:[0,1]
	v_add_f32_e32 v4, v4, v5
	v_xor_b32_e32 v4, 0x80000000, v4
	v_cvt_pk_bf16_f32 v4, v6, v4
	ds_read_b64 v[6:7], v103 offset:520
	ds_read_b64 v[8:9], v104 offset:16904
	s_waitcnt lgkmcnt(0)
	v_pk_mul_f32 v[10:11], v[6:7], v[8:9]
	v_pk_mul_f32 v[6:7], v[6:7], v[8:9] op_sel:[1,0] op_sel_hi:[0,1]
	v_add_f32_e32 v6, v6, v7
	v_sub_f32_e32 v5, v10, v11
	v_xor_b32_e32 v6, 0x80000000, v6
	v_cvt_pk_bf16_f32 v5, v5, v6
	ds_read_b64 v[6:7], v103 offset:528
	ds_read_b64 v[8:9], v104 offset:16912
	s_waitcnt lgkmcnt(0)
	v_pk_mul_f32 v[10:11], v[6:7], v[8:9]
	v_pk_mul_f32 v[6:7], v[6:7], v[8:9] op_sel:[1,0] op_sel_hi:[0,1]
	v_add_f32_e32 v6, v6, v7
	v_sub_f32_e32 v10, v10, v11
	v_xor_b32_e32 v6, 0x80000000, v6
	v_cvt_pk_bf16_f32 v6, v10, v6
	ds_read_b64 v[8:9], v103 offset:536
	ds_read_b64 v[10:11], v104 offset:16920
	s_waitcnt lgkmcnt(0)
	v_pk_mul_f32 v[12:13], v[8:9], v[10:11]
	v_pk_mul_f32 v[8:9], v[8:9], v[10:11] op_sel:[1,0] op_sel_hi:[0,1]
	v_add_f32_e32 v8, v8, v9
	v_sub_f32_e32 v7, v12, v13
	v_xor_b32_e32 v8, 0x80000000, v8
	v_cvt_pk_bf16_f32 v7, v7, v8
	ds_read_b64 v[8:9], v106 offset:512
	ds_read_b64 v[10:11], v107 offset:16896
	v_lshl_add_u64 v[12:13], v[2:3], 0, v[38:39]
	global_store_dwordx4 v[12:13], v[4:7], off nt
	v_lshl_add_u64 v[2:3], v[2:3], 0, v[40:41]
	s_waitcnt lgkmcnt(0)
	v_pk_mul_f32 v[4:5], v[8:9], v[10:11]
	s_nop 0
	v_sub_f32_e32 v6, v4, v5
	v_pk_mul_f32 v[4:5], v[8:9], v[10:11] op_sel:[1,0] op_sel_hi:[0,1]
	v_add_f32_e32 v4, v4, v5
	v_xor_b32_e32 v4, 0x80000000, v4
	v_cvt_pk_bf16_f32 v4, v6, v4
	ds_read_b64 v[6:7], v106 offset:520
	ds_read_b64 v[8:9], v107 offset:16904
	s_waitcnt lgkmcnt(0)
	v_pk_mul_f32 v[10:11], v[6:7], v[8:9]
	v_pk_mul_f32 v[6:7], v[6:7], v[8:9] op_sel:[1,0] op_sel_hi:[0,1]
	v_add_f32_e32 v6, v6, v7
	v_sub_f32_e32 v5, v10, v11
	v_xor_b32_e32 v6, 0x80000000, v6
	v_cvt_pk_bf16_f32 v5, v5, v6
	ds_read_b64 v[6:7], v106 offset:528
	ds_read_b64 v[8:9], v107 offset:16912
	s_waitcnt lgkmcnt(0)
	v_pk_mul_f32 v[10:11], v[6:7], v[8:9]
	v_pk_mul_f32 v[6:7], v[6:7], v[8:9] op_sel:[1,0] op_sel_hi:[0,1]
	v_add_f32_e32 v6, v6, v7
	v_sub_f32_e32 v10, v10, v11
	v_xor_b32_e32 v6, 0x80000000, v6
	v_cvt_pk_bf16_f32 v6, v10, v6
	ds_read_b64 v[8:9], v106 offset:536
	ds_read_b64 v[10:11], v107 offset:16920
	s_waitcnt lgkmcnt(0)
	v_pk_mul_f32 v[12:13], v[8:9], v[10:11]
	v_pk_mul_f32 v[8:9], v[8:9], v[10:11] op_sel:[1,0] op_sel_hi:[0,1]
	v_sub_f32_e32 v7, v12, v13
	v_add_f32_e32 v8, v8, v9
	v_xor_b32_e32 v8, 0x80000000, v8
	v_cvt_pk_bf16_f32 v7, v7, v8
	global_store_dwordx4 v[2:3], v[4:7], off nt
	ds_read_b64 v[16:17], v108
	ds_read_b128 v[4:7], v137 offset:8704
	v_lshl_add_u64 v[2:3], s[82:83], 0, v[20:21]
	ds_read_b128 v[8:11], v137 offset:8720
	ds_read_b128 v[12:15], v137 offset:8736
	ds_read_b128 v[146:149], v137 offset:8752
	v_lshl_add_u64 v[2:3], v[2:3], 0, s[80:81]
	s_waitcnt lgkmcnt(3)
	v_pk_mul_f32 v[150:151], v[16:17], v[4:5] op_sel:[0,1] op_sel_hi:[1,0]
	v_pk_mul_f32 v[4:5], v[16:17], v[4:5]
	v_add_f32_e32 v20, v150, v151
	v_sub_f32_e32 v4, v4, v5
	v_cndmask_b32_e64 v20, v20, v4, s[8:9]
	v_pk_mul_f32 v[4:5], v[16:17], v[6:7] op_sel:[0,1] op_sel_hi:[1,0]
	s_nop 0
	v_add_f32_e32 v79, v4, v5
	v_pk_mul_f32 v[4:5], v[16:17], v[6:7]
	s_nop 0
	v_sub_f32_e32 v4, v4, v5
	v_cndmask_b32_e64 v6, v79, v4, s[8:9]
	s_waitcnt lgkmcnt(2)
	v_pk_mul_f32 v[4:5], v[16:17], v[8:9] op_sel:[0,1] op_sel_hi:[1,0]
	s_nop 0
	v_add_f32_e32 v7, v4, v5
	v_pk_mul_f32 v[4:5], v[16:17], v[8:9]
	s_nop 0
	v_sub_f32_e32 v4, v4, v5
	v_cndmask_b32_e64 v7, v7, v4, s[8:9]
	v_pk_mul_f32 v[4:5], v[16:17], v[10:11] op_sel:[0,1] op_sel_hi:[1,0]
	s_nop 0
	v_add_f32_e32 v8, v4, v5
	v_pk_mul_f32 v[4:5], v[16:17], v[10:11]
	s_nop 0
	v_sub_f32_e32 v4, v4, v5
	v_cndmask_b32_e64 v8, v8, v4, s[8:9]
	s_waitcnt lgkmcnt(1)
	v_pk_mul_f32 v[4:5], v[16:17], v[12:13] op_sel:[0,1] op_sel_hi:[1,0]
	s_nop 0
	v_add_f32_e32 v9, v4, v5
	v_pk_mul_f32 v[4:5], v[16:17], v[12:13]
	s_nop 0
	v_sub_f32_e32 v4, v4, v5
	v_cndmask_b32_e64 v9, v9, v4, s[8:9]
	v_pk_mul_f32 v[4:5], v[16:17], v[14:15] op_sel:[0,1] op_sel_hi:[1,0]
	s_nop 0
	v_add_f32_e32 v10, v4, v5
	v_pk_mul_f32 v[4:5], v[16:17], v[14:15]
	s_nop 0
	v_sub_f32_e32 v4, v4, v5
	v_cndmask_b32_e64 v10, v10, v4, s[8:9]
	s_waitcnt lgkmcnt(0)
	v_pk_mul_f32 v[4:5], v[16:17], v[146:147] op_sel:[0,1] op_sel_hi:[1,0]
	s_nop 0
	v_add_f32_e32 v11, v4, v5
	v_pk_mul_f32 v[4:5], v[16:17], v[146:147]
	s_nop 0
	v_sub_f32_e32 v4, v4, v5
	v_cndmask_b32_e64 v11, v11, v4, s[8:9]
	v_pk_mul_f32 v[4:5], v[16:17], v[148:149] op_sel:[0,1] op_sel_hi:[1,0]
	s_nop 0
	v_add_f32_e32 v12, v4, v5
	v_pk_mul_f32 v[4:5], v[16:17], v[148:149]
	s_nop 0
	v_sub_f32_e32 v4, v4, v5
	v_cndmask_b32_e64 v12, v12, v4, s[8:9]
	v_cvt_pk_bf16_f32 v4, v20, v6
	v_cvt_pk_bf16_f32 v5, v7, v8
	v_cvt_pk_bf16_f32 v6, v9, v10
	v_cvt_pk_bf16_f32 v7, v11, v12
	ds_read_b64 v[16:17], v109
	ds_read_b128 v[8:11], v138 offset:8704
	v_lshl_add_u64 v[12:13], v[2:3], 0, v[42:43]
	global_store_dwordx4 v[12:13], v[4:7], off nt
	ds_read_b128 v[4:7], v138 offset:8720
	ds_read_b128 v[12:15], v138 offset:8736
	ds_read_b128 v[146:149], v138 offset:8752
	s_waitcnt lgkmcnt(3)
	v_pk_mul_f32 v[150:151], v[16:17], v[8:9] op_sel:[0,1] op_sel_hi:[1,0]
	v_pk_mul_f32 v[8:9], v[16:17], v[8:9]
	v_add_f32_e32 v20, v150, v151
	v_sub_f32_e32 v8, v8, v9
	v_cndmask_b32_e64 v20, v20, v8, s[8:9]
	v_pk_mul_f32 v[8:9], v[16:17], v[10:11] op_sel:[0,1] op_sel_hi:[1,0]
	s_nop 0
	v_add_f32_e32 v79, v8, v9
	v_pk_mul_f32 v[8:9], v[16:17], v[10:11]
	s_nop 0
	v_sub_f32_e32 v8, v8, v9
	v_cndmask_b32_e64 v10, v79, v8, s[8:9]
	s_waitcnt lgkmcnt(2)
	v_pk_mul_f32 v[8:9], v[16:17], v[4:5] op_sel:[0,1] op_sel_hi:[1,0]
	v_pk_mul_f32 v[4:5], v[16:17], v[4:5]
	v_add_f32_e32 v8, v8, v9
	v_sub_f32_e32 v4, v4, v5
	v_cndmask_b32_e64 v8, v8, v4, s[8:9]
	v_pk_mul_f32 v[4:5], v[16:17], v[6:7] op_sel:[0,1] op_sel_hi:[1,0]
	s_nop 0
	v_add_f32_e32 v9, v4, v5
	v_pk_mul_f32 v[4:5], v[16:17], v[6:7]
	s_nop 0
	v_sub_f32_e32 v4, v4, v5
	v_cndmask_b32_e64 v6, v9, v4, s[8:9]
	s_waitcnt lgkmcnt(1)
	v_pk_mul_f32 v[4:5], v[16:17], v[12:13] op_sel:[0,1] op_sel_hi:[1,0]
	s_nop 0
	v_add_f32_e32 v7, v4, v5
	v_pk_mul_f32 v[4:5], v[16:17], v[12:13]
	s_nop 0
	v_sub_f32_e32 v4, v4, v5
	v_cndmask_b32_e64 v7, v7, v4, s[8:9]
	v_pk_mul_f32 v[4:5], v[16:17], v[14:15] op_sel:[0,1] op_sel_hi:[1,0]
	s_nop 0
	v_add_f32_e32 v9, v4, v5
	v_pk_mul_f32 v[4:5], v[16:17], v[14:15]
	s_nop 0
	v_sub_f32_e32 v4, v4, v5
	v_cndmask_b32_e64 v9, v9, v4, s[8:9]
	s_waitcnt lgkmcnt(0)
	v_pk_mul_f32 v[4:5], v[16:17], v[146:147] op_sel:[0,1] op_sel_hi:[1,0]
	s_nop 0
	v_add_f32_e32 v11, v4, v5
	v_pk_mul_f32 v[4:5], v[16:17], v[146:147]
	s_nop 0
	v_sub_f32_e32 v4, v4, v5
	v_cndmask_b32_e64 v11, v11, v4, s[8:9]
	v_pk_mul_f32 v[4:5], v[16:17], v[148:149] op_sel:[0,1] op_sel_hi:[1,0]
	s_nop 0
	v_add_f32_e32 v12, v4, v5
	v_pk_mul_f32 v[4:5], v[16:17], v[148:149]
	s_nop 0
	v_sub_f32_e32 v4, v4, v5
	v_cndmask_b32_e64 v12, v12, v4, s[8:9]
	v_cvt_pk_bf16_f32 v4, v20, v10
	v_cvt_pk_bf16_f32 v5, v8, v6
	v_cvt_pk_bf16_f32 v6, v7, v9
	v_cvt_pk_bf16_f32 v7, v11, v12
	ds_read_b64 v[16:17], v110
	ds_read_b128 v[8:11], v139 offset:8704
	v_lshl_add_u64 v[12:13], v[2:3], 0, v[44:45]
	global_store_dwordx4 v[12:13], v[4:7], off nt
	ds_read_b128 v[4:7], v139 offset:8720
	ds_read_b128 v[12:15], v139 offset:8736
	ds_read_b128 v[146:149], v139 offset:8752
	s_waitcnt lgkmcnt(3)
	v_pk_mul_f32 v[150:151], v[16:17], v[8:9] op_sel:[0,1] op_sel_hi:[1,0]
	v_pk_mul_f32 v[8:9], v[16:17], v[8:9]
	v_add_f32_e32 v20, v150, v151
	v_sub_f32_e32 v8, v8, v9
	v_cndmask_b32_e64 v20, v20, v8, s[8:9]
	v_pk_mul_f32 v[8:9], v[16:17], v[10:11] op_sel:[0,1] op_sel_hi:[1,0]
	s_nop 0
	v_add_f32_e32 v79, v8, v9
	v_pk_mul_f32 v[8:9], v[16:17], v[10:11]
	s_nop 0
	v_sub_f32_e32 v8, v8, v9
	v_cndmask_b32_e64 v10, v79, v8, s[8:9]
	s_waitcnt lgkmcnt(2)
	v_pk_mul_f32 v[8:9], v[16:17], v[4:5] op_sel:[0,1] op_sel_hi:[1,0]
	v_pk_mul_f32 v[4:5], v[16:17], v[4:5]
	v_add_f32_e32 v8, v8, v9
	v_sub_f32_e32 v4, v4, v5
	v_cndmask_b32_e64 v8, v8, v4, s[8:9]
	v_pk_mul_f32 v[4:5], v[16:17], v[6:7] op_sel:[0,1] op_sel_hi:[1,0]
	s_nop 0
	v_add_f32_e32 v9, v4, v5
	v_pk_mul_f32 v[4:5], v[16:17], v[6:7]
	s_nop 0
	v_sub_f32_e32 v4, v4, v5
	v_cndmask_b32_e64 v6, v9, v4, s[8:9]
	s_waitcnt lgkmcnt(1)
	v_pk_mul_f32 v[4:5], v[16:17], v[12:13] op_sel:[0,1] op_sel_hi:[1,0]
	s_nop 0
	v_add_f32_e32 v7, v4, v5
	v_pk_mul_f32 v[4:5], v[16:17], v[12:13]
	s_nop 0
	v_sub_f32_e32 v4, v4, v5
	v_cndmask_b32_e64 v7, v7, v4, s[8:9]
	v_pk_mul_f32 v[4:5], v[16:17], v[14:15] op_sel:[0,1] op_sel_hi:[1,0]
	s_nop 0
	v_add_f32_e32 v9, v4, v5
	v_pk_mul_f32 v[4:5], v[16:17], v[14:15]
	s_nop 0
	v_sub_f32_e32 v4, v4, v5
	v_cndmask_b32_e64 v9, v9, v4, s[8:9]
	s_waitcnt lgkmcnt(0)
	v_pk_mul_f32 v[4:5], v[16:17], v[146:147] op_sel:[0,1] op_sel_hi:[1,0]
	s_nop 0
	v_add_f32_e32 v11, v4, v5
	v_pk_mul_f32 v[4:5], v[16:17], v[146:147]
	s_nop 0
	v_sub_f32_e32 v4, v4, v5
	v_cndmask_b32_e64 v11, v11, v4, s[8:9]
	v_pk_mul_f32 v[4:5], v[16:17], v[148:149] op_sel:[0,1] op_sel_hi:[1,0]
	s_nop 0
	v_add_f32_e32 v12, v4, v5
	v_pk_mul_f32 v[4:5], v[16:17], v[148:149]
	s_nop 0
	v_sub_f32_e32 v4, v4, v5
	v_cndmask_b32_e64 v12, v12, v4, s[8:9]
	v_cvt_pk_bf16_f32 v4, v20, v10
	v_cvt_pk_bf16_f32 v5, v8, v6
	v_cvt_pk_bf16_f32 v6, v7, v9
	v_cvt_pk_bf16_f32 v7, v11, v12
	ds_read_b64 v[16:17], v111
	ds_read_b128 v[8:11], v140 offset:8704
	v_lshl_add_u64 v[12:13], v[2:3], 0, v[46:47]
	global_store_dwordx4 v[12:13], v[4:7], off nt
	ds_read_b128 v[4:7], v140 offset:8720
	ds_read_b128 v[12:15], v140 offset:8736
	ds_read_b128 v[146:149], v140 offset:8752
	s_waitcnt lgkmcnt(3)
	v_pk_mul_f32 v[150:151], v[16:17], v[8:9] op_sel:[0,1] op_sel_hi:[1,0]
	v_pk_mul_f32 v[8:9], v[16:17], v[8:9]
	v_add_f32_e32 v20, v150, v151
	v_sub_f32_e32 v8, v8, v9
	v_cndmask_b32_e64 v20, v20, v8, s[8:9]
	v_pk_mul_f32 v[8:9], v[16:17], v[10:11] op_sel:[0,1] op_sel_hi:[1,0]
	s_nop 0
	v_add_f32_e32 v79, v8, v9
	v_pk_mul_f32 v[8:9], v[16:17], v[10:11]
	s_nop 0
	v_sub_f32_e32 v8, v8, v9
	v_cndmask_b32_e64 v10, v79, v8, s[8:9]
	s_waitcnt lgkmcnt(2)
	v_pk_mul_f32 v[8:9], v[16:17], v[4:5] op_sel:[0,1] op_sel_hi:[1,0]
	v_pk_mul_f32 v[4:5], v[16:17], v[4:5]
	v_add_f32_e32 v8, v8, v9
	v_sub_f32_e32 v4, v4, v5
	v_cndmask_b32_e64 v8, v8, v4, s[8:9]
	v_pk_mul_f32 v[4:5], v[16:17], v[6:7] op_sel:[0,1] op_sel_hi:[1,0]
	s_nop 0
	v_add_f32_e32 v9, v4, v5
	v_pk_mul_f32 v[4:5], v[16:17], v[6:7]
	s_nop 0
	v_sub_f32_e32 v4, v4, v5
	v_cndmask_b32_e64 v6, v9, v4, s[8:9]
	s_waitcnt lgkmcnt(1)
	v_pk_mul_f32 v[4:5], v[16:17], v[12:13] op_sel:[0,1] op_sel_hi:[1,0]
	s_nop 0
	v_add_f32_e32 v7, v4, v5
	v_pk_mul_f32 v[4:5], v[16:17], v[12:13]
	s_nop 0
	v_sub_f32_e32 v4, v4, v5
	v_cndmask_b32_e64 v7, v7, v4, s[8:9]
	v_pk_mul_f32 v[4:5], v[16:17], v[14:15] op_sel:[0,1] op_sel_hi:[1,0]
	s_nop 0
	v_add_f32_e32 v9, v4, v5
	v_pk_mul_f32 v[4:5], v[16:17], v[14:15]
	s_nop 0
	v_sub_f32_e32 v4, v4, v5
	v_cndmask_b32_e64 v9, v9, v4, s[8:9]
	s_waitcnt lgkmcnt(0)
	v_pk_mul_f32 v[4:5], v[16:17], v[146:147] op_sel:[0,1] op_sel_hi:[1,0]
	s_nop 0
	v_add_f32_e32 v11, v4, v5
	v_pk_mul_f32 v[4:5], v[16:17], v[146:147]
	s_nop 0
	v_sub_f32_e32 v4, v4, v5
	v_cndmask_b32_e64 v11, v11, v4, s[8:9]
	v_pk_mul_f32 v[4:5], v[16:17], v[148:149] op_sel:[0,1] op_sel_hi:[1,0]
	s_nop 0
	v_add_f32_e32 v12, v4, v5
	v_pk_mul_f32 v[4:5], v[16:17], v[148:149]
	s_nop 0
	v_sub_f32_e32 v4, v4, v5
	v_cndmask_b32_e64 v12, v12, v4, s[8:9]
	v_cvt_pk_bf16_f32 v4, v20, v10
	v_cvt_pk_bf16_f32 v5, v8, v6
	v_cvt_pk_bf16_f32 v6, v7, v9
	v_cvt_pk_bf16_f32 v7, v11, v12
	ds_read_b64 v[16:17], v112
	ds_read_b128 v[8:11], v141 offset:8704
	v_lshl_add_u64 v[12:13], v[2:3], 0, v[48:49]
	global_store_dwordx4 v[12:13], v[4:7], off nt
	ds_read_b128 v[4:7], v141 offset:8720
	ds_read_b128 v[12:15], v141 offset:8736
	ds_read_b128 v[146:149], v141 offset:8752
	s_waitcnt lgkmcnt(3)
	v_pk_mul_f32 v[150:151], v[16:17], v[8:9] op_sel:[0,1] op_sel_hi:[1,0]
	v_pk_mul_f32 v[8:9], v[16:17], v[8:9]
	v_add_f32_e32 v20, v150, v151
	v_sub_f32_e32 v8, v8, v9
	v_cndmask_b32_e64 v20, v20, v8, s[8:9]
	v_pk_mul_f32 v[8:9], v[16:17], v[10:11] op_sel:[0,1] op_sel_hi:[1,0]
	s_nop 0
	v_add_f32_e32 v79, v8, v9
	v_pk_mul_f32 v[8:9], v[16:17], v[10:11]
	s_nop 0
	v_sub_f32_e32 v8, v8, v9
	v_cndmask_b32_e64 v10, v79, v8, s[8:9]
	s_waitcnt lgkmcnt(2)
	v_pk_mul_f32 v[8:9], v[16:17], v[4:5] op_sel:[0,1] op_sel_hi:[1,0]
	v_pk_mul_f32 v[4:5], v[16:17], v[4:5]
	v_add_f32_e32 v8, v8, v9
	v_sub_f32_e32 v4, v4, v5
	v_cndmask_b32_e64 v8, v8, v4, s[8:9]
	v_pk_mul_f32 v[4:5], v[16:17], v[6:7] op_sel:[0,1] op_sel_hi:[1,0]
	s_nop 0
	v_add_f32_e32 v9, v4, v5
	v_pk_mul_f32 v[4:5], v[16:17], v[6:7]
	s_nop 0
	v_sub_f32_e32 v4, v4, v5
	v_cndmask_b32_e64 v6, v9, v4, s[8:9]
	s_waitcnt lgkmcnt(1)
	v_pk_mul_f32 v[4:5], v[16:17], v[12:13] op_sel:[0,1] op_sel_hi:[1,0]
	s_nop 0
	v_add_f32_e32 v7, v4, v5
	v_pk_mul_f32 v[4:5], v[16:17], v[12:13]
	s_nop 0
	v_sub_f32_e32 v4, v4, v5
	v_cndmask_b32_e64 v7, v7, v4, s[8:9]
	v_pk_mul_f32 v[4:5], v[16:17], v[14:15] op_sel:[0,1] op_sel_hi:[1,0]
	s_nop 0
	v_add_f32_e32 v9, v4, v5
	v_pk_mul_f32 v[4:5], v[16:17], v[14:15]
	s_nop 0
	v_sub_f32_e32 v4, v4, v5
	v_cndmask_b32_e64 v9, v9, v4, s[8:9]
	s_waitcnt lgkmcnt(0)
	v_pk_mul_f32 v[4:5], v[16:17], v[146:147] op_sel:[0,1] op_sel_hi:[1,0]
	s_nop 0
	v_add_f32_e32 v11, v4, v5
	v_pk_mul_f32 v[4:5], v[16:17], v[146:147]
	s_nop 0
	v_sub_f32_e32 v4, v4, v5
	v_cndmask_b32_e64 v11, v11, v4, s[8:9]
	v_pk_mul_f32 v[4:5], v[16:17], v[148:149] op_sel:[0,1] op_sel_hi:[1,0]
	s_nop 0
	v_add_f32_e32 v12, v4, v5
	v_pk_mul_f32 v[4:5], v[16:17], v[148:149]
	s_nop 0
	v_sub_f32_e32 v4, v4, v5
	v_cndmask_b32_e64 v12, v12, v4, s[8:9]
	v_cvt_pk_bf16_f32 v4, v20, v10
	v_cvt_pk_bf16_f32 v5, v8, v6
	v_cvt_pk_bf16_f32 v6, v7, v9
	v_cvt_pk_bf16_f32 v7, v11, v12
	ds_read_b64 v[16:17], v113
	ds_read_b128 v[8:11], v142 offset:8704
	v_lshl_add_u64 v[12:13], v[2:3], 0, v[50:51]
	global_store_dwordx4 v[12:13], v[4:7], off nt
	ds_read_b128 v[4:7], v142 offset:8720
	ds_read_b128 v[12:15], v142 offset:8736
	ds_read_b128 v[146:149], v142 offset:8752
	s_waitcnt lgkmcnt(3)
	v_pk_mul_f32 v[150:151], v[16:17], v[8:9] op_sel:[0,1] op_sel_hi:[1,0]
	v_pk_mul_f32 v[8:9], v[16:17], v[8:9]
	v_add_f32_e32 v20, v150, v151
	v_sub_f32_e32 v8, v8, v9
	v_cndmask_b32_e64 v20, v20, v8, s[8:9]
	v_pk_mul_f32 v[8:9], v[16:17], v[10:11] op_sel:[0,1] op_sel_hi:[1,0]
	s_nop 0
	v_add_f32_e32 v79, v8, v9
	v_pk_mul_f32 v[8:9], v[16:17], v[10:11]
	s_nop 0
	v_sub_f32_e32 v8, v8, v9
	v_cndmask_b32_e64 v10, v79, v8, s[8:9]
	s_waitcnt lgkmcnt(2)
	v_pk_mul_f32 v[8:9], v[16:17], v[4:5] op_sel:[0,1] op_sel_hi:[1,0]
	v_pk_mul_f32 v[4:5], v[16:17], v[4:5]
	v_add_f32_e32 v8, v8, v9
	v_sub_f32_e32 v4, v4, v5
	v_cndmask_b32_e64 v8, v8, v4, s[8:9]
	v_pk_mul_f32 v[4:5], v[16:17], v[6:7] op_sel:[0,1] op_sel_hi:[1,0]
	s_nop 0
	v_add_f32_e32 v9, v4, v5
	v_pk_mul_f32 v[4:5], v[16:17], v[6:7]
	s_nop 0
	v_sub_f32_e32 v4, v4, v5
	v_cndmask_b32_e64 v6, v9, v4, s[8:9]
	s_waitcnt lgkmcnt(1)
	v_pk_mul_f32 v[4:5], v[16:17], v[12:13] op_sel:[0,1] op_sel_hi:[1,0]
	s_nop 0
	v_add_f32_e32 v7, v4, v5
	v_pk_mul_f32 v[4:5], v[16:17], v[12:13]
	s_nop 0
	v_sub_f32_e32 v4, v4, v5
	v_cndmask_b32_e64 v7, v7, v4, s[8:9]
	v_pk_mul_f32 v[4:5], v[16:17], v[14:15] op_sel:[0,1] op_sel_hi:[1,0]
	s_nop 0
	v_add_f32_e32 v9, v4, v5
	v_pk_mul_f32 v[4:5], v[16:17], v[14:15]
	s_nop 0
	v_sub_f32_e32 v4, v4, v5
	v_cndmask_b32_e64 v9, v9, v4, s[8:9]
	s_waitcnt lgkmcnt(0)
	v_pk_mul_f32 v[4:5], v[16:17], v[146:147] op_sel:[0,1] op_sel_hi:[1,0]
	s_nop 0
	v_add_f32_e32 v11, v4, v5
	v_pk_mul_f32 v[4:5], v[16:17], v[146:147]
	s_nop 0
	v_sub_f32_e32 v4, v4, v5
	v_cndmask_b32_e64 v11, v11, v4, s[8:9]
	v_pk_mul_f32 v[4:5], v[16:17], v[148:149] op_sel:[0,1] op_sel_hi:[1,0]
	s_nop 0
	v_add_f32_e32 v12, v4, v5
	v_pk_mul_f32 v[4:5], v[16:17], v[148:149]
	s_nop 0
	v_sub_f32_e32 v4, v4, v5
	v_cndmask_b32_e64 v12, v12, v4, s[8:9]
	v_cvt_pk_bf16_f32 v4, v20, v10
	v_cvt_pk_bf16_f32 v5, v8, v6
	v_cvt_pk_bf16_f32 v6, v7, v9
	v_cvt_pk_bf16_f32 v7, v11, v12
	ds_read_b64 v[16:17], v114
	ds_read_b128 v[8:11], v143 offset:8704
	v_lshl_add_u64 v[12:13], v[2:3], 0, v[52:53]
	global_store_dwordx4 v[12:13], v[4:7], off nt
	ds_read_b128 v[4:7], v143 offset:8720
	ds_read_b128 v[12:15], v143 offset:8736
	ds_read_b128 v[146:149], v143 offset:8752
	s_waitcnt lgkmcnt(3)
	v_pk_mul_f32 v[150:151], v[16:17], v[8:9] op_sel:[0,1] op_sel_hi:[1,0]
	v_pk_mul_f32 v[8:9], v[16:17], v[8:9]
	v_add_f32_e32 v20, v150, v151
	v_sub_f32_e32 v8, v8, v9
	v_cndmask_b32_e64 v20, v20, v8, s[8:9]
	v_pk_mul_f32 v[8:9], v[16:17], v[10:11] op_sel:[0,1] op_sel_hi:[1,0]
	s_nop 0
	v_add_f32_e32 v79, v8, v9
	v_pk_mul_f32 v[8:9], v[16:17], v[10:11]
	s_nop 0
	v_sub_f32_e32 v8, v8, v9
	v_cndmask_b32_e64 v10, v79, v8, s[8:9]
	s_waitcnt lgkmcnt(2)
	v_pk_mul_f32 v[8:9], v[16:17], v[4:5] op_sel:[0,1] op_sel_hi:[1,0]
	v_pk_mul_f32 v[4:5], v[16:17], v[4:5]
	v_add_f32_e32 v8, v8, v9
	v_sub_f32_e32 v4, v4, v5
	v_cndmask_b32_e64 v8, v8, v4, s[8:9]
	v_pk_mul_f32 v[4:5], v[16:17], v[6:7] op_sel:[0,1] op_sel_hi:[1,0]
	s_nop 0
	v_add_f32_e32 v9, v4, v5
	v_pk_mul_f32 v[4:5], v[16:17], v[6:7]
	s_nop 0
	v_sub_f32_e32 v4, v4, v5
	v_cndmask_b32_e64 v6, v9, v4, s[8:9]
	s_waitcnt lgkmcnt(1)
	v_pk_mul_f32 v[4:5], v[16:17], v[12:13] op_sel:[0,1] op_sel_hi:[1,0]
	s_nop 0
	v_add_f32_e32 v7, v4, v5
	v_pk_mul_f32 v[4:5], v[16:17], v[12:13]
	s_nop 0
	v_sub_f32_e32 v4, v4, v5
	v_cndmask_b32_e64 v7, v7, v4, s[8:9]
	v_pk_mul_f32 v[4:5], v[16:17], v[14:15] op_sel:[0,1] op_sel_hi:[1,0]
	s_nop 0
	v_add_f32_e32 v9, v4, v5
	v_pk_mul_f32 v[4:5], v[16:17], v[14:15]
	s_nop 0
	v_sub_f32_e32 v4, v4, v5
	v_cndmask_b32_e64 v9, v9, v4, s[8:9]
	s_waitcnt lgkmcnt(0)
	v_pk_mul_f32 v[4:5], v[16:17], v[146:147] op_sel:[0,1] op_sel_hi:[1,0]
	s_nop 0
	v_add_f32_e32 v11, v4, v5
	v_pk_mul_f32 v[4:5], v[16:17], v[146:147]
	s_nop 0
	v_sub_f32_e32 v4, v4, v5
	v_cndmask_b32_e64 v11, v11, v4, s[8:9]
	v_pk_mul_f32 v[4:5], v[16:17], v[148:149] op_sel:[0,1] op_sel_hi:[1,0]
	s_nop 0
	v_add_f32_e32 v12, v4, v5
	v_pk_mul_f32 v[4:5], v[16:17], v[148:149]
	s_nop 0
	v_sub_f32_e32 v4, v4, v5
	v_cndmask_b32_e64 v12, v12, v4, s[8:9]
	v_cvt_pk_bf16_f32 v4, v20, v10
	v_cvt_pk_bf16_f32 v5, v8, v6
	v_cvt_pk_bf16_f32 v6, v7, v9
	v_cvt_pk_bf16_f32 v7, v11, v12
	ds_read_b64 v[16:17], v115
	ds_read_b128 v[8:11], v144 offset:8704
	v_lshl_add_u64 v[12:13], v[2:3], 0, v[54:55]
	global_store_dwordx4 v[12:13], v[4:7], off nt
	ds_read_b128 v[4:7], v144 offset:8720
	ds_read_b128 v[12:15], v144 offset:8736
	ds_read_b128 v[146:149], v144 offset:8752
	v_lshl_add_u64 v[2:3], v[2:3], 0, v[56:57]
	s_waitcnt lgkmcnt(3)
	v_pk_mul_f32 v[150:151], v[16:17], v[8:9] op_sel:[0,1] op_sel_hi:[1,0]
	v_pk_mul_f32 v[8:9], v[16:17], v[8:9]
	v_add_f32_e32 v20, v150, v151
	v_sub_f32_e32 v8, v8, v9
	v_cndmask_b32_e64 v20, v20, v8, s[8:9]
	v_pk_mul_f32 v[8:9], v[16:17], v[10:11] op_sel:[0,1] op_sel_hi:[1,0]
	s_nop 0
	v_add_f32_e32 v79, v8, v9
	v_pk_mul_f32 v[8:9], v[16:17], v[10:11]
	s_nop 0
	v_sub_f32_e32 v8, v8, v9
	v_cndmask_b32_e64 v10, v79, v8, s[8:9]
	s_waitcnt lgkmcnt(2)
	v_pk_mul_f32 v[8:9], v[16:17], v[4:5] op_sel:[0,1] op_sel_hi:[1,0]
	v_pk_mul_f32 v[4:5], v[16:17], v[4:5]
	v_add_f32_e32 v8, v8, v9
	v_sub_f32_e32 v4, v4, v5
	v_cndmask_b32_e64 v8, v8, v4, s[8:9]
	v_pk_mul_f32 v[4:5], v[16:17], v[6:7] op_sel:[0,1] op_sel_hi:[1,0]
	s_nop 0
	v_add_f32_e32 v9, v4, v5
	v_pk_mul_f32 v[4:5], v[16:17], v[6:7]
	s_nop 0
	v_sub_f32_e32 v4, v4, v5
	v_cndmask_b32_e64 v6, v9, v4, s[8:9]
	s_waitcnt lgkmcnt(1)
	v_pk_mul_f32 v[4:5], v[16:17], v[12:13] op_sel:[0,1] op_sel_hi:[1,0]
	s_nop 0
	v_add_f32_e32 v7, v4, v5
	v_pk_mul_f32 v[4:5], v[16:17], v[12:13]
	s_nop 0
	v_sub_f32_e32 v4, v4, v5
	v_cndmask_b32_e64 v7, v7, v4, s[8:9]
	v_pk_mul_f32 v[4:5], v[16:17], v[14:15] op_sel:[0,1] op_sel_hi:[1,0]
	s_nop 0
	v_add_f32_e32 v9, v4, v5
	v_pk_mul_f32 v[4:5], v[16:17], v[14:15]
	s_nop 0
	v_sub_f32_e32 v4, v4, v5
	v_cndmask_b32_e64 v9, v9, v4, s[8:9]
	s_waitcnt lgkmcnt(0)
	v_pk_mul_f32 v[4:5], v[16:17], v[146:147] op_sel:[0,1] op_sel_hi:[1,0]
	s_nop 0
	v_add_f32_e32 v11, v4, v5
	v_pk_mul_f32 v[4:5], v[16:17], v[146:147]
	s_nop 0
	v_sub_f32_e32 v4, v4, v5
	v_cndmask_b32_e64 v11, v11, v4, s[8:9]
	v_pk_mul_f32 v[4:5], v[16:17], v[148:149] op_sel:[0,1] op_sel_hi:[1,0]
	s_nop 0
	v_add_f32_e32 v12, v4, v5
	v_pk_mul_f32 v[4:5], v[16:17], v[148:149]
	s_nop 0
	v_sub_f32_e32 v4, v4, v5
	v_cndmask_b32_e64 v12, v12, v4, s[8:9]
	v_cvt_pk_bf16_f32 v4, v20, v10
	v_cvt_pk_bf16_f32 v5, v8, v6
	v_cvt_pk_bf16_f32 v6, v7, v9
	v_cvt_pk_bf16_f32 v7, v11, v12
	global_store_dwordx4 v[2:3], v[4:7], off nt

.LBB0_97:
	s_or_b64 exec, exec, s[68:69]
	ds_write_b32 v116, v4 offset:39424
	v_mov_b32_e32 v4, 0
	v_mov_b32_e32 v5, 0
	s_waitcnt lgkmcnt(0)
	s_barrier
	s_and_saveexec_b64 s[68:69], s[10:11]
	ds_read_b32 v5, v117 offset:25088
	s_or_b64 exec, exec, s[68:69]
	s_and_saveexec_b64 s[68:69], s[10:11]
	ds_read_b32 v4, v117 offset:25092
	s_or_b64 exec, exec, s[68:69]
	v_mov_b32_e32 v6, 0
	v_mov_b32_e32 v7, 0
	s_and_saveexec_b64 s[68:69], s[10:11]
	ds_read_b32 v7, v117 offset:25096
	s_or_b64 exec, exec, s[68:69]
	s_and_saveexec_b64 s[68:69], s[10:11]
	ds_read_b32 v6, v117 offset:25100
	s_or_b64 exec, exec, s[68:69]
	v_mov_b32_e32 v8, 0
	v_mov_b32_e32 v9, 0
	s_and_saveexec_b64 s[68:69], s[10:11]
	ds_read_b32 v9, v117 offset:25104
	s_or_b64 exec, exec, s[68:69]
	s_and_saveexec_b64 s[68:69], s[10:11]
	ds_read_b32 v8, v117 offset:25108
	s_or_b64 exec, exec, s[68:69]
	v_mov_b32_e32 v10, 0
	v_mov_b32_e32 v11, 0
	s_and_saveexec_b64 s[68:69], s[10:11]
	ds_read_b32 v11, v117 offset:25112
	s_or_b64 exec, exec, s[68:69]
	s_and_saveexec_b64 s[68:69], s[10:11]
	ds_read_b32 v10, v117 offset:25116
	s_or_b64 exec, exec, s[68:69]
	v_lshlrev_b32_e32 v20, 1, v22
	v_lshl_add_u64 v[2:3], s[82:83], 0, v[20:21]
	s_waitcnt lgkmcnt(0)
	v_cvt_pk_bf16_f32 v4, v5, v4
	v_cvt_pk_bf16_f32 v5, v7, v6
	v_cvt_pk_bf16_f32 v6, v9, v8
	v_lshl_add_u64 v[8:9], v[2:3], 0, v[42:43]
	v_cvt_pk_bf16_f32 v7, v11, v10
	global_store_dwordx4 v[8:9], v[4:7], off nt
	s_nop 1
	v_mov_b32_e32 v4, 0
	v_mov_b32_e32 v5, 0
	s_and_saveexec_b64 s[68:69], s[12:13]
	ds_read_b32 v5, v118 offset:25088
	s_or_b64 exec, exec, s[68:69]
	s_and_saveexec_b64 s[68:69], s[12:13]
	ds_read_b32 v4, v118 offset:25092
	s_or_b64 exec, exec, s[68:69]
	v_mov_b32_e32 v6, 0
	v_mov_b32_e32 v7, 0
	s_and_saveexec_b64 s[68:69], s[12:13]
	ds_read_b32 v7, v118 offset:25096
	s_or_b64 exec, exec, s[68:69]
	s_and_saveexec_b64 s[68:69], s[12:13]
	ds_read_b32 v6, v118 offset:25100
	s_or_b64 exec, exec, s[68:69]
	v_mov_b32_e32 v8, 0
	v_mov_b32_e32 v9, 0
	s_and_saveexec_b64 s[68:69], s[12:13]
	ds_read_b32 v9, v118 offset:25104
	s_or_b64 exec, exec, s[68:69]
	s_and_saveexec_b64 s[68:69], s[12:13]
	ds_read_b32 v8, v118 offset:25108
	s_or_b64 exec, exec, s[68:69]
	v_mov_b32_e32 v10, 0
	v_mov_b32_e32 v11, 0
	s_and_saveexec_b64 s[68:69], s[12:13]
	ds_read_b32 v11, v118 offset:25112
	s_or_b64 exec, exec, s[68:69]
	s_and_saveexec_b64 s[68:69], s[12:13]
	ds_read_b32 v10, v118 offset:25116
	s_or_b64 exec, exec, s[68:69]
	s_waitcnt lgkmcnt(0)
	v_cvt_pk_bf16_f32 v4, v5, v4
	v_cvt_pk_bf16_f32 v5, v7, v6
	v_cvt_pk_bf16_f32 v6, v9, v8
	v_lshl_add_u64 v[8:9], v[2:3], 0, v[44:45]
	v_cvt_pk_bf16_f32 v7, v11, v10
	global_store_dwordx4 v[8:9], v[4:7], off nt
	s_nop 1
	v_mov_b32_e32 v4, 0
	v_mov_b32_e32 v5, 0
	s_and_saveexec_b64 s[68:69], s[14:15]
	ds_read_b32 v5, v119 offset:25088
	s_or_b64 exec, exec, s[68:69]
	s_and_saveexec_b64 s[68:69], s[14:15]
	ds_read_b32 v4, v119 offset:25092
	s_or_b64 exec, exec, s[68:69]
	v_mov_b32_e32 v6, 0
	v_mov_b32_e32 v7, 0
	s_and_saveexec_b64 s[68:69], s[14:15]
	ds_read_b32 v7, v119 offset:25096
	s_or_b64 exec, exec, s[68:69]
	s_and_saveexec_b64 s[68:69], s[14:15]
	ds_read_b32 v6, v119 offset:25100
	s_or_b64 exec, exec, s[68:69]
	v_mov_b32_e32 v8, 0
	v_mov_b32_e32 v9, 0
	s_and_saveexec_b64 s[68:69], s[14:15]
	ds_read_b32 v9, v119 offset:25104
	s_or_b64 exec, exec, s[68:69]
	s_and_saveexec_b64 s[68:69], s[14:15]
	ds_read_b32 v8, v119 offset:25108
	s_or_b64 exec, exec, s[68:69]
	v_mov_b32_e32 v10, 0
	v_mov_b32_e32 v11, 0
	s_and_saveexec_b64 s[68:69], s[14:15]
	ds_read_b32 v11, v119 offset:25112
	s_or_b64 exec, exec, s[68:69]
	s_and_saveexec_b64 s[68:69], s[14:15]
	ds_read_b32 v10, v119 offset:25116
	s_or_b64 exec, exec, s[68:69]
	s_waitcnt lgkmcnt(0)
	v_cvt_pk_bf16_f32 v4, v5, v4
	v_cvt_pk_bf16_f32 v5, v7, v6
	v_cvt_pk_bf16_f32 v6, v9, v8
	v_lshl_add_u64 v[8:9], v[2:3], 0, v[46:47]
	v_cvt_pk_bf16_f32 v7, v11, v10
	global_store_dwordx4 v[8:9], v[4:7], off nt
	s_nop 1
	v_mov_b32_e32 v4, 0
	v_mov_b32_e32 v5, 0
	s_and_saveexec_b64 s[68:69], s[16:17]
	ds_read_b32 v5, v120 offset:25088
	s_or_b64 exec, exec, s[68:69]
	s_and_saveexec_b64 s[68:69], s[16:17]
	ds_read_b32 v4, v120 offset:25092
	s_or_b64 exec, exec, s[68:69]
	v_mov_b32_e32 v6, 0
	v_mov_b32_e32 v7, 0
	s_and_saveexec_b64 s[68:69], s[16:17]
	ds_read_b32 v7, v120 offset:25096
	s_or_b64 exec, exec, s[68:69]
	s_and_saveexec_b64 s[68:69], s[16:17]
	ds_read_b32 v6, v120 offset:25100
	s_or_b64 exec, exec, s[68:69]
	v_mov_b32_e32 v8, 0
	v_mov_b32_e32 v9, 0
	s_and_saveexec_b64 s[68:69], s[16:17]
	ds_read_b32 v9, v120 offset:25104
	s_or_b64 exec, exec, s[68:69]
	s_and_saveexec_b64 s[68:69], s[16:17]
	ds_read_b32 v8, v120 offset:25108
	s_or_b64 exec, exec, s[68:69]
	v_mov_b32_e32 v10, 0
	v_mov_b32_e32 v11, 0
	s_and_saveexec_b64 s[68:69], s[16:17]
	ds_read_b32 v11, v120 offset:25112
	s_or_b64 exec, exec, s[68:69]
	s_and_saveexec_b64 s[68:69], s[16:17]
	ds_read_b32 v10, v120 offset:25116
	s_or_b64 exec, exec, s[68:69]
	s_waitcnt lgkmcnt(0)
	v_cvt_pk_bf16_f32 v4, v5, v4
	v_cvt_pk_bf16_f32 v5, v7, v6
	v_cvt_pk_bf16_f32 v6, v9, v8
	v_lshl_add_u64 v[8:9], v[2:3], 0, v[48:49]
	v_cvt_pk_bf16_f32 v7, v11, v10
	global_store_dwordx4 v[8:9], v[4:7], off nt
	s_nop 1
	v_mov_b32_e32 v4, 0
	v_mov_b32_e32 v5, 0
	s_and_saveexec_b64 s[68:69], s[18:19]
	ds_read_b32 v5, v121 offset:25088
	s_or_b64 exec, exec, s[68:69]
	s_and_saveexec_b64 s[68:69], s[18:19]
	ds_read_b32 v4, v121 offset:25092
	s_or_b64 exec, exec, s[68:69]
	v_mov_b32_e32 v6, 0
	v_mov_b32_e32 v7, 0
	s_and_saveexec_b64 s[68:69], s[18:19]
	ds_read_b32 v7, v121 offset:25096
	s_or_b64 exec, exec, s[68:69]
	s_and_saveexec_b64 s[68:69], s[18:19]
	ds_read_b32 v6, v121 offset:25100
	s_or_b64 exec, exec, s[68:69]
	v_mov_b32_e32 v8, 0
	v_mov_b32_e32 v9, 0
	s_and_saveexec_b64 s[68:69], s[18:19]
	ds_read_b32 v9, v121 offset:25104
	s_or_b64 exec, exec, s[68:69]
	s_and_saveexec_b64 s[68:69], s[18:19]
	ds_read_b32 v8, v121 offset:25108
	s_or_b64 exec, exec, s[68:69]
	v_mov_b32_e32 v10, 0
	v_mov_b32_e32 v11, 0
	s_and_saveexec_b64 s[68:69], s[18:19]
	ds_read_b32 v11, v121 offset:25112
	s_or_b64 exec, exec, s[68:69]
	s_and_saveexec_b64 s[68:69], s[18:19]
	ds_read_b32 v10, v121 offset:25116
	s_or_b64 exec, exec, s[68:69]
	s_waitcnt lgkmcnt(0)
	v_cvt_pk_bf16_f32 v4, v5, v4
	v_cvt_pk_bf16_f32 v5, v7, v6
	v_cvt_pk_bf16_f32 v6, v9, v8
	v_lshl_add_u64 v[8:9], v[2:3], 0, v[50:51]
	v_cvt_pk_bf16_f32 v7, v11, v10
	global_store_dwordx4 v[8:9], v[4:7], off nt
	s_nop 1
	v_mov_b32_e32 v4, 0
	v_mov_b32_e32 v5, 0
	s_and_saveexec_b64 s[68:69], s[20:21]
	ds_read_b32 v5, v122 offset:25088
	s_or_b64 exec, exec, s[68:69]
	s_and_saveexec_b64 s[68:69], s[20:21]
	ds_read_b32 v4, v122 offset:25092
	s_or_b64 exec, exec, s[68:69]
	v_mov_b32_e32 v6, 0
	v_mov_b32_e32 v7, 0
	s_and_saveexec_b64 s[68:69], s[20:21]
	ds_read_b32 v7, v122 offset:25096
	s_or_b64 exec, exec, s[68:69]
	s_and_saveexec_b64 s[68:69], s[20:21]
	ds_read_b32 v6, v122 offset:25100
	s_or_b64 exec, exec, s[68:69]
	v_mov_b32_e32 v8, 0
	v_mov_b32_e32 v9, 0
	s_and_saveexec_b64 s[68:69], s[20:21]
	ds_read_b32 v9, v122 offset:25104
	s_or_b64 exec, exec, s[68:69]
	s_and_saveexec_b64 s[68:69], s[20:21]
	ds_read_b32 v8, v122 offset:25108
	s_or_b64 exec, exec, s[68:69]
	v_mov_b32_e32 v10, 0
	v_mov_b32_e32 v11, 0
	s_and_saveexec_b64 s[68:69], s[20:21]
	ds_read_b32 v11, v122 offset:25112
	s_or_b64 exec, exec, s[68:69]
	s_and_saveexec_b64 s[68:69], s[20:21]
	ds_read_b32 v10, v122 offset:25116
	s_or_b64 exec, exec, s[68:69]
	s_waitcnt lgkmcnt(0)
	v_cvt_pk_bf16_f32 v4, v5, v4
	v_cvt_pk_bf16_f32 v5, v7, v6
	v_cvt_pk_bf16_f32 v6, v9, v8
	v_lshl_add_u64 v[8:9], v[2:3], 0, v[52:53]
	v_cvt_pk_bf16_f32 v7, v11, v10
	global_store_dwordx4 v[8:9], v[4:7], off nt
	s_nop 1
	v_mov_b32_e32 v4, 0
	v_mov_b32_e32 v5, 0
	s_and_saveexec_b64 s[68:69], s[22:23]
	ds_read_b32 v5, v123 offset:25088
	s_or_b64 exec, exec, s[68:69]
	s_and_saveexec_b64 s[68:69], s[22:23]
	ds_read_b32 v4, v123 offset:25092
	s_or_b64 exec, exec, s[68:69]
	v_mov_b32_e32 v6, 0
	v_mov_b32_e32 v7, 0
	s_and_saveexec_b64 s[68:69], s[22:23]
	ds_read_b32 v7, v123 offset:25096
	s_or_b64 exec, exec, s[68:69]
	s_and_saveexec_b64 s[68:69], s[22:23]
	ds_read_b32 v6, v123 offset:25100
	s_or_b64 exec, exec, s[68:69]
	v_mov_b32_e32 v8, 0
	v_mov_b32_e32 v9, 0
	s_and_saveexec_b64 s[68:69], s[22:23]
	ds_read_b32 v9, v123 offset:25104
	s_or_b64 exec, exec, s[68:69]
	s_and_saveexec_b64 s[68:69], s[22:23]
	ds_read_b32 v8, v123 offset:25108
	s_or_b64 exec, exec, s[68:69]
	v_mov_b32_e32 v10, 0
	v_mov_b32_e32 v11, 0
	s_and_saveexec_b64 s[68:69], s[22:23]
	ds_read_b32 v11, v123 offset:25112
	s_or_b64 exec, exec, s[68:69]
	s_and_saveexec_b64 s[68:69], s[22:23]
	ds_read_b32 v10, v123 offset:25116
	s_or_b64 exec, exec, s[68:69]
	s_waitcnt lgkmcnt(0)
	v_cvt_pk_bf16_f32 v4, v5, v4
	v_cvt_pk_bf16_f32 v5, v7, v6
	v_cvt_pk_bf16_f32 v6, v9, v8
	v_lshl_add_u64 v[8:9], v[2:3], 0, v[54:55]
	v_cvt_pk_bf16_f32 v7, v11, v10
	global_store_dwordx4 v[8:9], v[4:7], off nt
	s_nop 1
	v_mov_b32_e32 v4, 0
	v_mov_b32_e32 v5, 0
	s_and_saveexec_b64 s[68:69], s[24:25]
	ds_read_b32 v5, v124 offset:25088
	s_or_b64 exec, exec, s[68:69]
	s_and_saveexec_b64 s[68:69], s[24:25]
	ds_read_b32 v4, v124 offset:25092
	s_or_b64 exec, exec, s[68:69]
	v_mov_b32_e32 v6, 0
	v_mov_b32_e32 v7, 0
	s_and_saveexec_b64 s[68:69], s[24:25]
	ds_read_b32 v7, v124 offset:25096
	s_or_b64 exec, exec, s[68:69]
	s_and_saveexec_b64 s[68:69], s[24:25]
	ds_read_b32 v6, v124 offset:25100
	s_or_b64 exec, exec, s[68:69]
	v_mov_b32_e32 v8, 0
	v_mov_b32_e32 v9, 0
	s_and_saveexec_b64 s[68:69], s[24:25]
	ds_read_b32 v9, v124 offset:25104
	s_or_b64 exec, exec, s[68:69]
	s_and_saveexec_b64 s[68:69], s[24:25]
	ds_read_b32 v8, v124 offset:25108
	s_or_b64 exec, exec, s[68:69]
	v_mov_b32_e32 v10, 0
	v_mov_b32_e32 v11, 0
	s_and_saveexec_b64 s[68:69], s[24:25]
	ds_read_b32 v11, v124 offset:25112
	s_or_b64 exec, exec, s[68:69]
	s_and_saveexec_b64 s[68:69], s[24:25]
	ds_read_b32 v10, v124 offset:25116
	s_or_b64 exec, exec, s[68:69]
	s_waitcnt lgkmcnt(0)
	v_cvt_pk_bf16_f32 v4, v5, v4
	v_cvt_pk_bf16_f32 v5, v7, v6
	v_cvt_pk_bf16_f32 v6, v9, v8
	v_lshl_add_u64 v[8:9], v[2:3], 0, v[56:57]
	v_cvt_pk_bf16_f32 v7, v11, v10
	global_store_dwordx4 v[8:9], v[4:7], off nt
	s_nop 1
	v_mov_b32_e32 v4, 0
	v_mov_b32_e32 v5, 0
	s_and_saveexec_b64 s[68:69], s[26:27]
	ds_read_b32 v5, v125 offset:25088
	s_or_b64 exec, exec, s[68:69]
	s_and_saveexec_b64 s[68:69], s[26:27]
	ds_read_b32 v4, v125 offset:25092
	s_or_b64 exec, exec, s[68:69]
	v_mov_b32_e32 v6, 0
	v_mov_b32_e32 v7, 0
	s_and_saveexec_b64 s[68:69], s[26:27]
	ds_read_b32 v7, v125 offset:25096
	s_or_b64 exec, exec, s[68:69]
	s_and_saveexec_b64 s[68:69], s[26:27]
	ds_read_b32 v6, v125 offset:25100
	s_or_b64 exec, exec, s[68:69]
	v_mov_b32_e32 v8, 0
	v_mov_b32_e32 v9, 0
	s_and_saveexec_b64 s[68:69], s[26:27]
	ds_read_b32 v9, v125 offset:25104
	s_or_b64 exec, exec, s[68:69]
	s_and_saveexec_b64 s[68:69], s[26:27]
	ds_read_b32 v8, v125 offset:25108
	s_or_b64 exec, exec, s[68:69]
	v_mov_b32_e32 v10, 0
	v_mov_b32_e32 v11, 0
	s_and_saveexec_b64 s[68:69], s[26:27]
	ds_read_b32 v11, v125 offset:25112
	s_or_b64 exec, exec, s[68:69]
	s_and_saveexec_b64 s[68:69], s[26:27]
	ds_read_b32 v10, v125 offset:25116
	s_or_b64 exec, exec, s[68:69]
	s_waitcnt lgkmcnt(0)
	v_cvt_pk_bf16_f32 v4, v5, v4
	v_cvt_pk_bf16_f32 v5, v7, v6
	v_cvt_pk_bf16_f32 v6, v9, v8
	v_lshl_add_u64 v[8:9], v[2:3], 0, v[58:59]
	v_cvt_pk_bf16_f32 v7, v11, v10
	global_store_dwordx4 v[8:9], v[4:7], off nt
	s_nop 1
	v_mov_b32_e32 v4, 0
	v_mov_b32_e32 v5, 0
	s_and_saveexec_b64 s[68:69], s[28:29]
	ds_read_b32 v5, v126 offset:25088
	s_or_b64 exec, exec, s[68:69]
	s_and_saveexec_b64 s[68:69], s[28:29]
	ds_read_b32 v4, v126 offset:25092
	s_or_b64 exec, exec, s[68:69]
	v_mov_b32_e32 v6, 0
	v_mov_b32_e32 v7, 0
	s_and_saveexec_b64 s[68:69], s[28:29]
	ds_read_b32 v7, v126 offset:25096
	s_or_b64 exec, exec, s[68:69]
	s_and_saveexec_b64 s[68:69], s[28:29]
	ds_read_b32 v6, v126 offset:25100
	s_or_b64 exec, exec, s[68:69]
	v_mov_b32_e32 v8, 0
	v_mov_b32_e32 v9, 0
	s_and_saveexec_b64 s[68:69], s[28:29]
	ds_read_b32 v9, v126 offset:25104
	s_or_b64 exec, exec, s[68:69]
	s_and_saveexec_b64 s[68:69], s[28:29]
	ds_read_b32 v8, v126 offset:25108
	s_or_b64 exec, exec, s[68:69]
	v_mov_b32_e32 v10, 0
	v_mov_b32_e32 v11, 0
	s_and_saveexec_b64 s[68:69], s[28:29]
	ds_read_b32 v11, v126 offset:25112
	s_or_b64 exec, exec, s[68:69]
	s_and_saveexec_b64 s[68:69], s[28:29]
	ds_read_b32 v10, v126 offset:25116
	s_or_b64 exec, exec, s[68:69]
	s_waitcnt lgkmcnt(0)
	v_cvt_pk_bf16_f32 v4, v5, v4
	v_cvt_pk_bf16_f32 v5, v7, v6
	v_cvt_pk_bf16_f32 v6, v9, v8
	v_lshl_add_u64 v[8:9], v[2:3], 0, v[60:61]
	v_cvt_pk_bf16_f32 v7, v11, v10
	global_store_dwordx4 v[8:9], v[4:7], off nt
	s_nop 1
	v_mov_b32_e32 v4, 0
	v_mov_b32_e32 v5, 0
	s_and_saveexec_b64 s[68:69], s[30:31]
	ds_read_b32 v5, v127 offset:25088
	s_or_b64 exec, exec, s[68:69]
	s_and_saveexec_b64 s[68:69], s[30:31]
	ds_read_b32 v4, v127 offset:25092
	s_or_b64 exec, exec, s[68:69]
	v_mov_b32_e32 v6, 0
	v_mov_b32_e32 v7, 0
	s_and_saveexec_b64 s[68:69], s[30:31]
	ds_read_b32 v7, v127 offset:25096
	s_or_b64 exec, exec, s[68:69]
	s_and_saveexec_b64 s[68:69], s[30:31]
	ds_read_b32 v6, v127 offset:25100
	s_or_b64 exec, exec, s[68:69]
	v_mov_b32_e32 v8, 0
	v_mov_b32_e32 v9, 0
	s_and_saveexec_b64 s[68:69], s[30:31]
	ds_read_b32 v9, v127 offset:25104
	s_or_b64 exec, exec, s[68:69]
	s_and_saveexec_b64 s[68:69], s[30:31]
	ds_read_b32 v8, v127 offset:25108
	s_or_b64 exec, exec, s[68:69]
	v_mov_b32_e32 v10, 0
	v_mov_b32_e32 v11, 0
	s_and_saveexec_b64 s[68:69], s[30:31]
	ds_read_b32 v11, v127 offset:25112
	s_or_b64 exec, exec, s[68:69]
	s_and_saveexec_b64 s[68:69], s[30:31]
	ds_read_b32 v10, v127 offset:25116
	s_or_b64 exec, exec, s[68:69]
	s_waitcnt lgkmcnt(0)
	v_cvt_pk_bf16_f32 v4, v5, v4
	v_cvt_pk_bf16_f32 v5, v7, v6
	v_cvt_pk_bf16_f32 v6, v9, v8
	v_lshl_add_u64 v[8:9], v[2:3], 0, v[62:63]
	v_cvt_pk_bf16_f32 v7, v11, v10
	global_store_dwordx4 v[8:9], v[4:7], off nt
	s_nop 1
	v_mov_b32_e32 v4, 0
	v_mov_b32_e32 v5, 0
	s_and_saveexec_b64 s[68:69], s[34:35]
	ds_read_b32 v5, v128 offset:25088
	s_or_b64 exec, exec, s[68:69]
	s_and_saveexec_b64 s[68:69], s[34:35]
	ds_read_b32 v4, v128 offset:25092
	s_or_b64 exec, exec, s[68:69]
	v_mov_b32_e32 v6, 0
	v_mov_b32_e32 v7, 0
	s_and_saveexec_b64 s[68:69], s[34:35]
	ds_read_b32 v7, v128 offset:25096
	s_or_b64 exec, exec, s[68:69]
	s_and_saveexec_b64 s[68:69], s[34:35]
	ds_read_b32 v6, v128 offset:25100
	s_or_b64 exec, exec, s[68:69]
	v_mov_b32_e32 v8, 0
	v_mov_b32_e32 v9, 0
	s_and_saveexec_b64 s[68:69], s[34:35]
	ds_read_b32 v9, v128 offset:25104
	s_or_b64 exec, exec, s[68:69]
	s_and_saveexec_b64 s[68:69], s[34:35]
	ds_read_b32 v8, v128 offset:25108
	s_or_b64 exec, exec, s[68:69]
	v_mov_b32_e32 v10, 0
	v_mov_b32_e32 v11, 0
	s_and_saveexec_b64 s[68:69], s[34:35]
	ds_read_b32 v11, v128 offset:25112
	s_or_b64 exec, exec, s[68:69]
	s_and_saveexec_b64 s[68:69], s[34:35]
	ds_read_b32 v10, v128 offset:25116
	s_or_b64 exec, exec, s[68:69]
	s_waitcnt lgkmcnt(0)
	v_cvt_pk_bf16_f32 v4, v5, v4
	v_cvt_pk_bf16_f32 v5, v7, v6
	v_cvt_pk_bf16_f32 v6, v9, v8
	v_lshl_add_u64 v[8:9], v[2:3], 0, v[64:65]
	v_cvt_pk_bf16_f32 v7, v11, v10
	global_store_dwordx4 v[8:9], v[4:7], off nt
	s_nop 1
	v_mov_b32_e32 v4, 0
	v_mov_b32_e32 v5, 0
	s_and_saveexec_b64 s[68:69], s[36:37]
	ds_read_b32 v5, v129 offset:25088
	s_or_b64 exec, exec, s[68:69]
	s_and_saveexec_b64 s[68:69], s[36:37]
	ds_read_b32 v4, v129 offset:25092
	s_or_b64 exec, exec, s[68:69]
	v_mov_b32_e32 v6, 0
	v_mov_b32_e32 v7, 0
	s_and_saveexec_b64 s[68:69], s[36:37]
	ds_read_b32 v7, v129 offset:25096
	s_or_b64 exec, exec, s[68:69]
	s_and_saveexec_b64 s[68:69], s[36:37]
	ds_read_b32 v6, v129 offset:25100
	s_or_b64 exec, exec, s[68:69]
	v_mov_b32_e32 v8, 0
	v_mov_b32_e32 v9, 0
	s_and_saveexec_b64 s[68:69], s[36:37]
	ds_read_b32 v9, v129 offset:25104
	s_or_b64 exec, exec, s[68:69]
	s_and_saveexec_b64 s[68:69], s[36:37]
	ds_read_b32 v8, v129 offset:25108
	s_or_b64 exec, exec, s[68:69]
	v_mov_b32_e32 v10, 0
	v_mov_b32_e32 v11, 0
	s_and_saveexec_b64 s[68:69], s[36:37]
	ds_read_b32 v11, v129 offset:25112
	s_or_b64 exec, exec, s[68:69]
	s_and_saveexec_b64 s[68:69], s[36:37]
	ds_read_b32 v10, v129 offset:25116
	s_or_b64 exec, exec, s[68:69]
	s_waitcnt lgkmcnt(0)
	v_cvt_pk_bf16_f32 v4, v5, v4
	v_cvt_pk_bf16_f32 v5, v7, v6
	v_cvt_pk_bf16_f32 v6, v9, v8
	v_lshl_add_u64 v[8:9], v[2:3], 0, v[66:67]
	v_cvt_pk_bf16_f32 v7, v11, v10
	global_store_dwordx4 v[8:9], v[4:7], off nt
	s_nop 1
	v_mov_b32_e32 v4, 0
	v_mov_b32_e32 v5, 0
	s_and_saveexec_b64 s[68:69], s[38:39]
	ds_read_b32 v5, v130 offset:25088
	s_or_b64 exec, exec, s[68:69]
	s_and_saveexec_b64 s[68:69], s[38:39]
	ds_read_b32 v4, v130 offset:25092
	s_or_b64 exec, exec, s[68:69]
	v_mov_b32_e32 v6, 0
	v_mov_b32_e32 v7, 0
	s_and_saveexec_b64 s[68:69], s[38:39]
	ds_read_b32 v7, v130 offset:25096
	s_or_b64 exec, exec, s[68:69]
	s_and_saveexec_b64 s[68:69], s[38:39]
	ds_read_b32 v6, v130 offset:25100
	s_or_b64 exec, exec, s[68:69]
	v_mov_b32_e32 v8, 0
	v_mov_b32_e32 v9, 0
	s_and_saveexec_b64 s[68:69], s[38:39]
	ds_read_b32 v9, v130 offset:25104
	s_or_b64 exec, exec, s[68:69]
	s_and_saveexec_b64 s[68:69], s[38:39]
	ds_read_b32 v8, v130 offset:25108
	s_or_b64 exec, exec, s[68:69]
	v_mov_b32_e32 v10, 0
	v_mov_b32_e32 v11, 0
	s_and_saveexec_b64 s[68:69], s[38:39]
	ds_read_b32 v11, v130 offset:25112
	s_or_b64 exec, exec, s[68:69]
	s_and_saveexec_b64 s[68:69], s[38:39]
	ds_read_b32 v10, v130 offset:25116
	s_or_b64 exec, exec, s[68:69]
	s_waitcnt lgkmcnt(0)
	v_cvt_pk_bf16_f32 v4, v5, v4
	v_cvt_pk_bf16_f32 v5, v7, v6
	v_cvt_pk_bf16_f32 v6, v9, v8
	v_lshl_add_u64 v[8:9], v[2:3], 0, v[68:69]
	v_cvt_pk_bf16_f32 v7, v11, v10
	global_store_dwordx4 v[8:9], v[4:7], off nt
	s_nop 1
	v_mov_b32_e32 v4, 0
	v_mov_b32_e32 v5, 0
	s_and_saveexec_b64 s[68:69], s[40:41]
	ds_read_b32 v5, v131 offset:25088
	s_or_b64 exec, exec, s[68:69]
	s_and_saveexec_b64 s[68:69], s[40:41]
	ds_read_b32 v4, v131 offset:25092
	s_or_b64 exec, exec, s[68:69]
	v_mov_b32_e32 v6, 0
	v_mov_b32_e32 v7, 0
	s_and_saveexec_b64 s[68:69], s[40:41]
	ds_read_b32 v7, v131 offset:25096
	s_or_b64 exec, exec, s[68:69]
	s_and_saveexec_b64 s[68:69], s[40:41]
	ds_read_b32 v6, v131 offset:25100
	s_or_b64 exec, exec, s[68:69]
	v_mov_b32_e32 v8, 0
	v_mov_b32_e32 v9, 0
	s_and_saveexec_b64 s[68:69], s[40:41]
	ds_read_b32 v9, v131 offset:25104
	s_or_b64 exec, exec, s[68:69]
	s_and_saveexec_b64 s[68:69], s[40:41]
	ds_read_b32 v8, v131 offset:25108
	s_or_b64 exec, exec, s[68:69]
	v_mov_b32_e32 v10, 0
	v_mov_b32_e32 v11, 0
	s_and_saveexec_b64 s[68:69], s[40:41]
	ds_read_b32 v11, v131 offset:25112
	s_or_b64 exec, exec, s[68:69]
	s_and_saveexec_b64 s[68:69], s[40:41]
	ds_read_b32 v10, v131 offset:25116
	s_or_b64 exec, exec, s[68:69]
	s_waitcnt lgkmcnt(0)
	v_cvt_pk_bf16_f32 v4, v5, v4
	v_cvt_pk_bf16_f32 v5, v7, v6
	v_cvt_pk_bf16_f32 v6, v9, v8
	v_lshl_add_u64 v[8:9], v[2:3], 0, v[70:71]
	v_cvt_pk_bf16_f32 v7, v11, v10
	global_store_dwordx4 v[8:9], v[4:7], off nt
	s_nop 1
	v_mov_b32_e32 v4, 0
	v_mov_b32_e32 v5, 0
	s_and_saveexec_b64 s[68:69], s[42:43]
	ds_read_b32 v5, v132 offset:25088
	s_or_b64 exec, exec, s[68:69]
	s_and_saveexec_b64 s[68:69], s[42:43]
	ds_read_b32 v4, v132 offset:25092
	s_or_b64 exec, exec, s[68:69]
	v_mov_b32_e32 v6, 0
	v_mov_b32_e32 v7, 0
	s_and_saveexec_b64 s[68:69], s[42:43]
	ds_read_b32 v7, v132 offset:25096
	s_or_b64 exec, exec, s[68:69]
	s_and_saveexec_b64 s[68:69], s[42:43]
	ds_read_b32 v6, v132 offset:25100
	s_or_b64 exec, exec, s[68:69]
	v_mov_b32_e32 v8, 0
	v_mov_b32_e32 v9, 0
	s_and_saveexec_b64 s[68:69], s[42:43]
	ds_read_b32 v9, v132 offset:25104
	s_or_b64 exec, exec, s[68:69]
	s_and_saveexec_b64 s[68:69], s[42:43]
	ds_read_b32 v8, v132 offset:25108
	s_or_b64 exec, exec, s[68:69]
	v_mov_b32_e32 v10, 0
	v_mov_b32_e32 v11, 0
	s_and_saveexec_b64 s[68:69], s[42:43]
	ds_read_b32 v11, v132 offset:25112
	s_or_b64 exec, exec, s[68:69]
	s_and_saveexec_b64 s[68:69], s[42:43]
	s_cbranch_execz .LBB0_69
	ds_read_b32 v10, v132 offset:25116
	s_branch .LBB0_69
